# hoist + peeled first iteration with srcC=0 (no accumulator zeroing v_movs) in P8/P9
# speedup vs baseline: 1.0042x; 1.0042x over previous
;     __host__ __device__ bool next(int i, Unit& u) const { const int L = i * G + c; if (L >= n) return false; u.pm = L; u.pn = L >> 2; return true; }
; #define PG8_STAGE(bufoff, gbase, voff) do { _Pragma("unroll") for (int _i = 0; _i < 2; ++_i) \
;         __builtin_amdgcn_global_load_lds((const unsigned*)((const char*)(gbase) + (voff)[_i]), (PG8_LAS unsigned*)(lds + (bufoff) + ldsw + _i * 8192), 16, 0, 0); } while (0)
; #define PG8_LDA(dst, b, h) do { _Pragma("unroll") for (int m = 0; m < 4; ++m) _Pragma("unroll") for (int k = 0; k < 2; ++k) dst[m][k] = *(const PG8_LAS bf16x8*)(lds + PG8_SA(b, h) + aoff + m * 2048 + k * 1024); } while (0)
; #define PG8_LDB(dst, b, h) do { _Pragma("unroll") for (int n = 0; n < 2; ++n) _Pragma("unroll") for (int k = 0; k < 2; ++k) dst[n][k] = *(const PG8_LAS bf16x8*)(lds + PG8_SB(b, h) + boff + n * 2048 + k * 1024); } while (0)
; #define PG8_WAIT_V(n) asm volatile("s_waitcnt vmcnt(" #n ")" ::: "memory")
; template <class Epi, class Sched, bool ALIGN_EPI>
; __device__ __forceinline__ void gemm_phase(PG8_LAS unsigned char* lds, const Gemm g, const Sched& S, const Epi& E) {
;     ...
;         const bool has_next = S.next(ui + 1, nxt);
;         const size_t tail_ = has_next ? 0 : tailoff; const char* nA = (has_next ? (const char*)g.A + (size_t)nxt.pm * tstepA : cA) + (has_next ? 0 : tailoffA); const char* nB = (has_next ? (const char*)g.Bt + (size_t)nxt.pn * tstepB : cB) + tail_;
;         for (int t = 0; t < nt; t += 2) {
;             if constexpr (Epi::MIDK) { if (t == (nt >> 1)) E.midk(acc, cur, wr, fr); }
;             const bool last = (t == nt - 2);
;             const char* a1 = cA + (size_t)(t + 1) * kstepA;
;             const char* a2 = last ? nA : cA + (size_t)(t + 2) * kstepA; const char* b2 = last ? nB : cB + (size_t)(t + 2) * kstep;
;             const char* a3 = a2 + kstepA; const char* b3 = b2 + kstep;
;             PG8_LDB(B0, 0, 0); PG8_LDB(B1, 0, 1); PG8_SCHED; PG8_LDA(At, 0, 0); PG8_STAGE(PG8_SA(1, 1), a1 + hstepA, voffA);
;             PG8_WAIT_V(8); PG8_WAIT_L(0); PG8_BAR; PG8_MMA(0, 0, At, B0); PG8_MMA(0, 1, At, B1); PG8_BAR; PG8_SCHED;
;     ...
;         for (int a = 0; a < 2; ++a)
; #pragma unroll
;             for (int b = 0; b < 2; ++b)
; #pragma unroll
;                 for (int m = 0; m < 4; ++m)
; #pragma unroll
;                     for (int n = 0; n < 2; ++n) acc[a][b][m][n] = (f32x4){0.f, 0.f, 0.f, 0.f};
.LBB0_900:
	s_ashr_i32 s21, s20, 31
	s_lshl_b64 s[22:23], s[20:21], 20
	s_add_u32 s2, s68, s22
	s_addc_u32 s19, s69, s23
	s_and_b64 s[22:23], s[0:1], exec
	s_cselect_b32 s2, s2, s28
	s_cselect_b32 s19, s19, s29
	s_add_u32 s22, s2, s24
	s_addc_u32 s23, s19, s25
	s_ashr_i32 s19, s18, 31
	s_lshl_b64 s[34:35], s[18:19], 20
	s_add_u32 s2, s78, s34
	s_addc_u32 s19, s79, s35
	s_and_b64 s[34:35], s[0:1], exec
	s_cselect_b32 s2, s2, s30
	s_cselect_b32 s19, s19, s31
	s_add_u32 s24, s2, s24
	s_addc_u32 s25, s19, s25
	s_add_u32 s28, s28, 0x80080
	s_addc_u32 s29, s29, 0
	s_add_u32 s19, s30, 0x100
	s_addc_u32 s21, s31, 0
	s_mov_b32 s49, -2
	s_and_b32 s2, s3, 0xfff
	s_mov_b32 s49, 0
	s_cmp_lt_u32 s3, 0x1000
	s_cbranch_scc0 .Lp8k_B_init
	s_mov_b64 s[50:51], s[24:25]
	s_cmp_eq_u32 s42, 1
	s_cbranch_scc1 .Lp8k_A_first
	s_add_u32 s28, s30, 0x100
	s_addc_u32 s29, s31, 0
	ds_read_b128 v[156:159], v153 offset:0
	ds_read_b128 v[160:163], v153 offset:1024
	s_branch .Lp8k_A_entry
.Lp8k_A_first:
	s_add_u32 s28, s30, 0x80
	s_addc_u32 s29, s31, 0
	ds_read_b128 v[190:193], v155 offset:0
	ds_read_b128 v[194:197], v155 offset:1024
	ds_read_b128 v[198:201], v155 offset:2048
	s_add_i32 m0, s2, 0x18000
	s_nop 0
	global_load_lds_dwordx4 v134, s[28:29]
	ds_read_b128 v[202:205], v155 offset:3072
	ds_read_b128 v[206:209], v155 offset:4096
	ds_read_b128 v[210:213], v155 offset:5120
	s_add_i32 m0, s2, 0x1a000
	s_nop 0
	global_load_lds_dwordx4 v130, s[28:29]
	ds_read_b128 v[214:217], v155 offset:6144
	ds_read_b128 v[218:221], v155 offset:7168
	ds_read_b128 v[156:159], v153 offset:0
	s_add_u32 s30, s28, 0x20000
	s_addc_u32 s31, s29, 0
	s_add_i32 m0, s2, 0x19000
	s_nop 0
	global_load_lds_dwordx4 v134, s[30:31]
	ds_read_b128 v[160:163], v153 offset:1024
	ds_read_b128 v[164:167], v153 offset:2048
	ds_read_b128 v[168:171], v153 offset:3072
	s_add_i32 m0, s2, 0x1b000
	s_nop 0
	global_load_lds_dwordx4 v130, s[30:31]
	ds_read_b128 v[174:177], v153 offset:16384
	ds_read_b128 v[178:181], v153 offset:17408
	ds_read_b128 v[182:185], v153 offset:18432
	s_add_u32 s30, s28, 0x80000
	s_addc_u32 s31, s29, 0
	s_add_i32 m0, s2, 0x1c000
	s_nop 0
	global_load_lds_dwordx4 v134, s[30:31]
	ds_read_b128 v[186:189], v153 offset:19456
	ds_read_b128 v[222:225], v155 offset:16384
	ds_read_b128 v[226:229], v155 offset:17408
	s_add_i32 m0, s2, 0x1e000
	s_nop 0
	global_load_lds_dwordx4 v130, s[30:31]
	ds_read_b128 v[230:233], v155 offset:18432
	ds_read_b128 v[234:237], v155 offset:19456
	ds_read_b128 v[238:241], v155 offset:20480
	s_add_u32 s30, s28, 0xa0000
	s_addc_u32 s31, s29, 0
	s_add_i32 m0, s2, 0x1d000
	s_nop 0
	global_load_lds_dwordx4 v134, s[30:31]
	ds_read_b128 v[242:245], v155 offset:21504
	ds_read_b128 v[246:249], v155 offset:22528
	ds_read_b128 v[250:253], v155 offset:23552
	s_add_i32 m0, s2, 0x1f000
	s_nop 0
	global_load_lds_dwordx4 v130, s[30:31]
	s_add_u32 s28, s28, 0x80
	s_addc_u32 s29, s29, 0
.Lp8k_A_entry:
	s_waitcnt vmcnt(8) lgkmcnt(0)
	s_barrier
	s_setprio 1
	v_mfma_f32_16x16x32_bf16 v[126:129], v[156:159], v[190:193], 0
	v_mfma_f32_16x16x32_bf16 v[126:129], v[160:163], v[194:197], v[126:129]
	v_mfma_f32_16x16x32_bf16 v[122:125], v[168:171], v[194:197], 0
	v_mfma_f32_16x16x32_bf16 v[122:125], v[164:167], v[190:193], v[122:125]
	v_mfma_f32_16x16x32_bf16 v[118:121], v[174:177], v[190:193], 0
	v_mfma_f32_16x16x32_bf16 v[118:121], v[178:181], v[194:197], v[118:121]
	v_mfma_f32_16x16x32_bf16 v[114:117], v[186:189], v[194:197], 0
	v_mfma_f32_16x16x32_bf16 v[114:117], v[182:185], v[190:193], v[114:117]
	v_mfma_f32_16x16x32_bf16 v[98:101], v[182:185], v[198:201], 0
	v_mfma_f32_16x16x32_bf16 v[98:101], v[186:189], v[202:205], v[98:101]
	v_mfma_f32_16x16x32_bf16 v[102:105], v[178:181], v[202:205], 0
	v_mfma_f32_16x16x32_bf16 v[102:105], v[174:177], v[198:201], v[102:105]
	v_mfma_f32_16x16x32_bf16 v[106:109], v[164:167], v[198:201], 0
	v_mfma_f32_16x16x32_bf16 v[106:109], v[168:171], v[202:205], v[106:109]
	v_mfma_f32_16x16x32_bf16 v[110:113], v[160:163], v[202:205], 0
	v_mfma_f32_16x16x32_bf16 v[110:113], v[156:159], v[198:201], v[110:113]
	v_mfma_f32_16x16x32_bf16 v[94:97], v[156:159], v[206:209], 0
	v_mfma_f32_16x16x32_bf16 v[94:97], v[160:163], v[210:213], v[94:97]
	v_mfma_f32_16x16x32_bf16 v[90:93], v[168:171], v[210:213], 0
	v_mfma_f32_16x16x32_bf16 v[90:93], v[164:167], v[206:209], v[90:93]
	v_mfma_f32_16x16x32_bf16 v[86:89], v[174:177], v[206:209], 0
	v_mfma_f32_16x16x32_bf16 v[86:89], v[178:181], v[210:213], v[86:89]
	v_mfma_f32_16x16x32_bf16 v[82:85], v[186:189], v[210:213], 0
	v_mfma_f32_16x16x32_bf16 v[82:85], v[182:185], v[206:209], v[82:85]
	v_mfma_f32_16x16x32_bf16 v[66:69], v[182:185], v[214:217], 0
	v_mfma_f32_16x16x32_bf16 v[66:69], v[186:189], v[218:221], v[66:69]
	v_mfma_f32_16x16x32_bf16 v[70:73], v[178:181], v[218:221], 0
	v_mfma_f32_16x16x32_bf16 v[70:73], v[174:177], v[214:217], v[70:73]
	v_mfma_f32_16x16x32_bf16 v[74:77], v[164:167], v[214:217], 0
	v_mfma_f32_16x16x32_bf16 v[74:77], v[168:171], v[218:221], v[74:77]
	v_mfma_f32_16x16x32_bf16 v[78:81], v[160:163], v[218:221], 0
	v_mfma_f32_16x16x32_bf16 v[78:81], v[156:159], v[214:217], v[78:81]
	v_mfma_f32_16x16x32_bf16 v[62:65], v[156:159], v[222:225], 0
	v_mfma_f32_16x16x32_bf16 v[62:65], v[160:163], v[226:229], v[62:65]
	v_mfma_f32_16x16x32_bf16 v[58:61], v[168:171], v[226:229], 0
	v_mfma_f32_16x16x32_bf16 v[58:61], v[164:167], v[222:225], v[58:61]
	v_mfma_f32_16x16x32_bf16 v[54:57], v[174:177], v[222:225], 0
	v_mfma_f32_16x16x32_bf16 v[54:57], v[178:181], v[226:229], v[54:57]
	v_mfma_f32_16x16x32_bf16 v[50:53], v[186:189], v[226:229], 0
	v_mfma_f32_16x16x32_bf16 v[50:53], v[182:185], v[222:225], v[50:53]
; #define PG8_STAGE(bufoff, gbase, voff) do { _Pragma("unroll") for (int _i = 0; _i < 2; ++_i) \
;         __builtin_amdgcn_global_load_lds((const unsigned*)((const char*)(gbase) + (voff)[_i]), (PG8_LAS unsigned*)(lds + (bufoff) + ldsw + _i * 8192), 16, 0, 0); } while (0)
; #define PG8_LDA(dst, b, h) do { _Pragma("unroll") for (int m = 0; m < 4; ++m) _Pragma("unroll") for (int k = 0; k < 2; ++k) dst[m][k] = *(const PG8_LAS bf16x8*)(lds + PG8_SA(b, h) + aoff + m * 2048 + k * 1024); } while (0)
; #define PG8_LDB(dst, b, h) do { _Pragma("unroll") for (int n = 0; n < 2; ++n) _Pragma("unroll") for (int k = 0; k < 2; ++k) dst[n][k] = *(const PG8_LAS bf16x8*)(lds + PG8_SB(b, h) + boff + n * 2048 + k * 1024); } while (0)
; #define PG8_MMA(ai, bj, At, Bt) do { __builtin_amdgcn_s_setprio(1); _Pragma("unroll") for (int m = 0; m < 4; ++m) _Pragma("unroll") for (int n = 0; n < 2; ++n) _Pragma("unroll") for (int k = 0; k < 2; ++k) \
;         acc[ai][bj][m][n] = __builtin_amdgcn_mfma_f32_16x16x32_bf16(Bt[n][k], At[m][k], acc[ai][bj][m][n], 0, 0, 0); __builtin_amdgcn_s_setprio(0); } while (0)
; #define PG8_WAIT_V(n) asm volatile("s_waitcnt vmcnt(" #n ")" ::: "memory")
; #define PG8_WAIT_L(n) asm volatile("s_waitcnt lgkmcnt(" #n ")" ::: "memory")
; #define PG8_BAR __builtin_amdgcn_s_barrier()
; #define PG8_SCHED __builtin_amdgcn_sched_barrier(0)
; template <class Epi, class Sched, bool ALIGN_EPI>
; __device__ __forceinline__ void gemm_phase(PG8_LAS unsigned char* lds, const Gemm g, const Sched& S, const Epi& E) {
;     ...
;             PG8_WAIT_V(8); PG8_WAIT_L(0); PG8_BAR; PG8_MMA(0, 0, At, B0); PG8_MMA(0, 1, At, B1); PG8_BAR; PG8_SCHED;
;             PG8_LDA(At, 0, 1); PG8_STAGE(PG8_SB(0, 0), b2, voffB); PG8_STAGE(PG8_SB(0, 1), b2 + hstepB, voffB); PG8_STAGE(PG8_SA(0, 0), a2, voffA);
;             PG8_WAIT_V(8); PG8_WAIT_L(0); PG8_BAR; PG8_MMA(1, 0, At, B0); PG8_MMA(1, 1, At, B1); PG8_BAR; PG8_SCHED;
;             PG8_LDB(B0, 1, 0); PG8_LDB(B1, 1, 1); PG8_SCHED; PG8_LDA(At, 1, 0); PG8_STAGE(PG8_SA(0, 1), a2 + hstepA, voffA);
;             PG8_WAIT_V(8); PG8_WAIT_L(0); PG8_BAR; PG8_MMA(0, 0, At, B0); PG8_MMA(0, 1, At, B1); PG8_BAR; PG8_SCHED;
	v_mfma_f32_16x16x32_bf16 v[34:37], v[182:185], v[230:233], 0
	v_mfma_f32_16x16x32_bf16 v[34:37], v[186:189], v[234:237], v[34:37]
	v_mfma_f32_16x16x32_bf16 v[38:41], v[178:181], v[234:237], 0
	v_mfma_f32_16x16x32_bf16 v[38:41], v[174:177], v[230:233], v[38:41]
	v_mfma_f32_16x16x32_bf16 v[42:45], v[164:167], v[230:233], 0
	v_mfma_f32_16x16x32_bf16 v[42:45], v[168:171], v[234:237], v[42:45]
	v_mfma_f32_16x16x32_bf16 v[46:49], v[160:163], v[234:237], 0
	v_mfma_f32_16x16x32_bf16 v[46:49], v[156:159], v[230:233], v[46:49]
	v_mfma_f32_16x16x32_bf16 v[30:33], v[156:159], v[238:241], 0
	v_mfma_f32_16x16x32_bf16 v[30:33], v[160:163], v[242:245], v[30:33]
	v_mfma_f32_16x16x32_bf16 v[26:29], v[168:171], v[242:245], 0
	v_mfma_f32_16x16x32_bf16 v[26:29], v[164:167], v[238:241], v[26:29]
	v_mfma_f32_16x16x32_bf16 v[22:25], v[174:177], v[238:241], 0
	v_mfma_f32_16x16x32_bf16 v[22:25], v[178:181], v[242:245], v[22:25]
	v_mfma_f32_16x16x32_bf16 v[18:21], v[186:189], v[242:245], 0
	v_mfma_f32_16x16x32_bf16 v[18:21], v[182:185], v[238:241], v[18:21]
	v_mfma_f32_16x16x32_bf16 v[2:5], v[182:185], v[246:249], 0
	v_mfma_f32_16x16x32_bf16 v[2:5], v[186:189], v[250:253], v[2:5]
	v_mfma_f32_16x16x32_bf16 v[6:9], v[178:181], v[250:253], 0
	v_mfma_f32_16x16x32_bf16 v[6:9], v[174:177], v[246:249], v[6:9]
	v_mfma_f32_16x16x32_bf16 v[10:13], v[164:167], v[246:249], 0
	v_mfma_f32_16x16x32_bf16 v[10:13], v[168:171], v[250:253], v[10:13]
	v_mfma_f32_16x16x32_bf16 v[14:17], v[160:163], v[250:253], 0
	v_mfma_f32_16x16x32_bf16 v[14:17], v[156:159], v[246:249], v[14:17]
	s_setprio 0
	s_waitcnt vmcnt(0)
	s_barrier
	ds_read_b128 v[190:193], v155 offset:32768
	ds_read_b128 v[194:197], v155 offset:33792
	ds_read_b128 v[198:201], v155 offset:34816
	s_cmp_eq_u32 s49, 15
	s_cselect_b32 s28, s50, s28
	s_cselect_b32 s29, s51, s29
	s_add_i32 m0, s2, 0x10000
	s_nop 0
	global_load_lds_dwordx4 v134, s[28:29]
	ds_read_b128 v[202:205], v155 offset:35840
	ds_read_b128 v[206:209], v155 offset:36864
	ds_read_b128 v[210:213], v155 offset:37888
	s_add_i32 m0, s2, 0x12000
	s_nop 0
	global_load_lds_dwordx4 v130, s[28:29]
	ds_read_b128 v[214:217], v155 offset:38912
	ds_read_b128 v[218:221], v155 offset:39936
	ds_read_b128 v[156:159], v153 offset:32768
	s_add_u32 s30, s28, 0x20000
	s_addc_u32 s31, s29, 0
	s_add_i32 m0, s2, 0x11000
	s_nop 0
	global_load_lds_dwordx4 v134, s[30:31]
	ds_read_b128 v[160:163], v153 offset:33792
	ds_read_b128 v[164:167], v153 offset:34816
	ds_read_b128 v[168:171], v153 offset:35840
	s_add_i32 m0, s2, 0x13000
	s_nop 0
	global_load_lds_dwordx4 v130, s[30:31]
	ds_read_b128 v[174:177], v153 offset:49152
	ds_read_b128 v[178:181], v153 offset:50176
	ds_read_b128 v[182:185], v153 offset:51200
	s_add_u32 s30, s28, 0x80000
	s_addc_u32 s31, s29, 0
	s_add_i32 m0, s2, 0x14000
	s_nop 0
	global_load_lds_dwordx4 v134, s[30:31]
	ds_read_b128 v[186:189], v153 offset:52224
	ds_read_b128 v[222:225], v155 offset:49152
	ds_read_b128 v[226:229], v155 offset:50176
	s_add_i32 m0, s2, 0x16000
	s_nop 0
	global_load_lds_dwordx4 v130, s[30:31]
	ds_read_b128 v[230:233], v155 offset:51200
	ds_read_b128 v[234:237], v155 offset:52224
	ds_read_b128 v[238:241], v155 offset:53248
	s_add_u32 s30, s28, 0xa0000
	s_addc_u32 s31, s29, 0
	s_add_i32 m0, s2, 0x15000
	s_nop 0
	global_load_lds_dwordx4 v134, s[30:31]
	ds_read_b128 v[242:245], v155 offset:54272
	ds_read_b128 v[246:249], v155 offset:55296
	ds_read_b128 v[250:253], v155 offset:56320
	s_add_i32 m0, s2, 0x17000
	s_nop 0
	global_load_lds_dwordx4 v130, s[30:31]
	s_add_u32 s28, s28, 0x80
	s_addc_u32 s29, s29, 0
	s_waitcnt vmcnt(8) lgkmcnt(0)
	s_barrier
	s_setprio 1
	v_mfma_f32_16x16x32_bf16 v[126:129], v[156:159], v[190:193], v[126:129]
	v_mfma_f32_16x16x32_bf16 v[126:129], v[160:163], v[194:197], v[126:129]
	v_mfma_f32_16x16x32_bf16 v[122:125], v[168:171], v[194:197], v[122:125]
	v_mfma_f32_16x16x32_bf16 v[122:125], v[164:167], v[190:193], v[122:125]
	v_mfma_f32_16x16x32_bf16 v[118:121], v[174:177], v[190:193], v[118:121]
	v_mfma_f32_16x16x32_bf16 v[118:121], v[178:181], v[194:197], v[118:121]
	v_mfma_f32_16x16x32_bf16 v[114:117], v[186:189], v[194:197], v[114:117]
	v_mfma_f32_16x16x32_bf16 v[114:117], v[182:185], v[190:193], v[114:117]
	v_mfma_f32_16x16x32_bf16 v[98:101], v[182:185], v[198:201], v[98:101]
	v_mfma_f32_16x16x32_bf16 v[98:101], v[186:189], v[202:205], v[98:101]
	v_mfma_f32_16x16x32_bf16 v[102:105], v[178:181], v[202:205], v[102:105]
	v_mfma_f32_16x16x32_bf16 v[102:105], v[174:177], v[198:201], v[102:105]
	v_mfma_f32_16x16x32_bf16 v[106:109], v[164:167], v[198:201], v[106:109]
	v_mfma_f32_16x16x32_bf16 v[106:109], v[168:171], v[202:205], v[106:109]
	v_mfma_f32_16x16x32_bf16 v[110:113], v[160:163], v[202:205], v[110:113]
	v_mfma_f32_16x16x32_bf16 v[110:113], v[156:159], v[198:201], v[110:113]
	v_mfma_f32_16x16x32_bf16 v[94:97], v[156:159], v[206:209], v[94:97]
	v_mfma_f32_16x16x32_bf16 v[94:97], v[160:163], v[210:213], v[94:97]
	v_mfma_f32_16x16x32_bf16 v[90:93], v[168:171], v[210:213], v[90:93]
	v_mfma_f32_16x16x32_bf16 v[90:93], v[164:167], v[206:209], v[90:93]
	v_mfma_f32_16x16x32_bf16 v[86:89], v[174:177], v[206:209], v[86:89]
	v_mfma_f32_16x16x32_bf16 v[86:89], v[178:181], v[210:213], v[86:89]
	v_mfma_f32_16x16x32_bf16 v[82:85], v[186:189], v[210:213], v[82:85]
	v_mfma_f32_16x16x32_bf16 v[82:85], v[182:185], v[206:209], v[82:85]
	v_mfma_f32_16x16x32_bf16 v[66:69], v[182:185], v[214:217], v[66:69]
	v_mfma_f32_16x16x32_bf16 v[66:69], v[186:189], v[218:221], v[66:69]
	v_mfma_f32_16x16x32_bf16 v[70:73], v[178:181], v[218:221], v[70:73]
	v_mfma_f32_16x16x32_bf16 v[70:73], v[174:177], v[214:217], v[70:73]
	v_mfma_f32_16x16x32_bf16 v[74:77], v[164:167], v[214:217], v[74:77]
; #define PG8_STAGE(bufoff, gbase, voff) do { _Pragma("unroll") for (int _i = 0; _i < 2; ++_i) \
;         __builtin_amdgcn_global_load_lds((const unsigned*)((const char*)(gbase) + (voff)[_i]), (PG8_LAS unsigned*)(lds + (bufoff) + ldsw + _i * 8192), 16, 0, 0); } while (0)
; #define PG8_LDA(dst, b, h) do { _Pragma("unroll") for (int m = 0; m < 4; ++m) _Pragma("unroll") for (int k = 0; k < 2; ++k) dst[m][k] = *(const PG8_LAS bf16x8*)(lds + PG8_SA(b, h) + aoff + m * 2048 + k * 1024); } while (0)
; #define PG8_LDB(dst, b, h) do { _Pragma("unroll") for (int n = 0; n < 2; ++n) _Pragma("unroll") for (int k = 0; k < 2; ++k) dst[n][k] = *(const PG8_LAS bf16x8*)(lds + PG8_SB(b, h) + boff + n * 2048 + k * 1024); } while (0)
; #define PG8_MMA(ai, bj, At, Bt) do { __builtin_amdgcn_s_setprio(1); _Pragma("unroll") for (int m = 0; m < 4; ++m) _Pragma("unroll") for (int n = 0; n < 2; ++n) _Pragma("unroll") for (int k = 0; k < 2; ++k) \
;         acc[ai][bj][m][n] = __builtin_amdgcn_mfma_f32_16x16x32_bf16(Bt[n][k], At[m][k], acc[ai][bj][m][n], 0, 0, 0); __builtin_amdgcn_s_setprio(0); } while (0)
; #define PG8_WAIT_V(n) asm volatile("s_waitcnt vmcnt(" #n ")" ::: "memory")
; #define PG8_WAIT_L(n) asm volatile("s_waitcnt lgkmcnt(" #n ")" ::: "memory")
; #define PG8_BAR __builtin_amdgcn_s_barrier()
; #define PG8_SCHED __builtin_amdgcn_sched_barrier(0)
; template <class Epi, class Sched, bool ALIGN_EPI>
; __device__ __forceinline__ void gemm_phase(PG8_LAS unsigned char* lds, const Gemm g, const Sched& S, const Epi& E) {
;     ...
;             PG8_WAIT_V(8); PG8_WAIT_L(0); PG8_BAR; PG8_MMA(1, 0, At, B0); PG8_MMA(1, 1, At, B1); PG8_BAR; PG8_SCHED;
;             PG8_LDB(B0, 1, 0); PG8_LDB(B1, 1, 1); PG8_SCHED; PG8_LDA(At, 1, 0); PG8_STAGE(PG8_SA(0, 1), a2 + hstepA, voffA);
;             PG8_WAIT_V(8); PG8_WAIT_L(0); PG8_BAR; PG8_MMA(0, 0, At, B0); PG8_MMA(0, 1, At, B1); PG8_BAR; PG8_SCHED;
;             PG8_LDA(At, 1, 1); PG8_STAGE(PG8_SB(1, 0), b3, voffB); PG8_STAGE(PG8_SB(1, 1), b3 + hstepB, voffB); PG8_STAGE(PG8_SA(1, 0), a3, voffA);
;             PG8_WAIT_V(8); PG8_WAIT_L(0); PG8_BAR; PG8_MMA(1, 0, At, B0); PG8_MMA(1, 1, At, B1); PG8_BAR; PG8_SCHED;
	v_mfma_f32_16x16x32_bf16 v[74:77], v[168:171], v[218:221], v[74:77]
	v_mfma_f32_16x16x32_bf16 v[78:81], v[160:163], v[218:221], v[78:81]
	v_mfma_f32_16x16x32_bf16 v[78:81], v[156:159], v[214:217], v[78:81]
	v_mfma_f32_16x16x32_bf16 v[62:65], v[156:159], v[222:225], v[62:65]
	v_mfma_f32_16x16x32_bf16 v[62:65], v[160:163], v[226:229], v[62:65]
	v_mfma_f32_16x16x32_bf16 v[58:61], v[168:171], v[226:229], v[58:61]
	v_mfma_f32_16x16x32_bf16 v[58:61], v[164:167], v[222:225], v[58:61]
	v_mfma_f32_16x16x32_bf16 v[54:57], v[174:177], v[222:225], v[54:57]
	v_mfma_f32_16x16x32_bf16 v[54:57], v[178:181], v[226:229], v[54:57]
	v_mfma_f32_16x16x32_bf16 v[50:53], v[186:189], v[226:229], v[50:53]
	v_mfma_f32_16x16x32_bf16 v[50:53], v[182:185], v[222:225], v[50:53]
	v_mfma_f32_16x16x32_bf16 v[34:37], v[182:185], v[230:233], v[34:37]
	v_mfma_f32_16x16x32_bf16 v[34:37], v[186:189], v[234:237], v[34:37]
	v_mfma_f32_16x16x32_bf16 v[38:41], v[178:181], v[234:237], v[38:41]
	v_mfma_f32_16x16x32_bf16 v[38:41], v[174:177], v[230:233], v[38:41]
	v_mfma_f32_16x16x32_bf16 v[42:45], v[164:167], v[230:233], v[42:45]
	v_mfma_f32_16x16x32_bf16 v[42:45], v[168:171], v[234:237], v[42:45]
	v_mfma_f32_16x16x32_bf16 v[46:49], v[160:163], v[234:237], v[46:49]
	v_mfma_f32_16x16x32_bf16 v[46:49], v[156:159], v[230:233], v[46:49]
	v_mfma_f32_16x16x32_bf16 v[30:33], v[156:159], v[238:241], v[30:33]
	v_mfma_f32_16x16x32_bf16 v[30:33], v[160:163], v[242:245], v[30:33]
	v_mfma_f32_16x16x32_bf16 v[26:29], v[168:171], v[242:245], v[26:29]
	v_mfma_f32_16x16x32_bf16 v[26:29], v[164:167], v[238:241], v[26:29]
	v_mfma_f32_16x16x32_bf16 v[22:25], v[174:177], v[238:241], v[22:25]
	v_mfma_f32_16x16x32_bf16 v[22:25], v[178:181], v[242:245], v[22:25]
	v_mfma_f32_16x16x32_bf16 v[18:21], v[186:189], v[242:245], v[18:21]
	v_mfma_f32_16x16x32_bf16 v[18:21], v[182:185], v[238:241], v[18:21]
	v_mfma_f32_16x16x32_bf16 v[2:5], v[182:185], v[246:249], v[2:5]
	v_mfma_f32_16x16x32_bf16 v[2:5], v[186:189], v[250:253], v[2:5]
	v_mfma_f32_16x16x32_bf16 v[6:9], v[178:181], v[250:253], v[6:9]
	v_mfma_f32_16x16x32_bf16 v[6:9], v[174:177], v[246:249], v[6:9]
	v_mfma_f32_16x16x32_bf16 v[10:13], v[164:167], v[246:249], v[10:13]
	v_mfma_f32_16x16x32_bf16 v[10:13], v[168:171], v[250:253], v[10:13]
	v_mfma_f32_16x16x32_bf16 v[14:17], v[160:163], v[250:253], v[14:17]
	v_mfma_f32_16x16x32_bf16 v[14:17], v[156:159], v[246:249], v[14:17]
	s_setprio 0
	s_waitcnt vmcnt(0)
	s_barrier
	s_add_i32 s49, s49, 1
.Lp8k_A_loop:
	ds_read_b128 v[190:193], v155 offset:0
	ds_read_b128 v[194:197], v155 offset:1024
	ds_read_b128 v[198:201], v155 offset:2048
	s_add_i32 m0, s2, 0x18000
	s_nop 0
	global_load_lds_dwordx4 v134, s[28:29]
	ds_read_b128 v[202:205], v155 offset:3072
	ds_read_b128 v[206:209], v155 offset:4096
	ds_read_b128 v[210:213], v155 offset:5120
	s_add_i32 m0, s2, 0x1a000
	s_nop 0
	global_load_lds_dwordx4 v130, s[28:29]
	ds_read_b128 v[214:217], v155 offset:6144
	ds_read_b128 v[218:221], v155 offset:7168
	ds_read_b128 v[156:159], v153 offset:0
	s_add_u32 s30, s28, 0x20000
	s_addc_u32 s31, s29, 0
	s_add_i32 m0, s2, 0x19000
	s_nop 0
	global_load_lds_dwordx4 v134, s[30:31]
	ds_read_b128 v[160:163], v153 offset:1024
	ds_read_b128 v[164:167], v153 offset:2048
	ds_read_b128 v[168:171], v153 offset:3072
	s_add_i32 m0, s2, 0x1b000
	s_nop 0
	global_load_lds_dwordx4 v130, s[30:31]
	ds_read_b128 v[174:177], v153 offset:16384
	ds_read_b128 v[178:181], v153 offset:17408
	ds_read_b128 v[182:185], v153 offset:18432
	s_add_u32 s30, s28, 0x80000
	s_addc_u32 s31, s29, 0
	s_add_i32 m0, s2, 0x1c000
	s_nop 0
	global_load_lds_dwordx4 v134, s[30:31]
	ds_read_b128 v[186:189], v153 offset:19456
	ds_read_b128 v[222:225], v155 offset:16384
	ds_read_b128 v[226:229], v155 offset:17408
	s_add_i32 m0, s2, 0x1e000
	s_nop 0
	global_load_lds_dwordx4 v130, s[30:31]
	ds_read_b128 v[230:233], v155 offset:18432
	ds_read_b128 v[234:237], v155 offset:19456
	ds_read_b128 v[238:241], v155 offset:20480
	s_add_u32 s30, s28, 0xa0000
	s_addc_u32 s31, s29, 0
	s_add_i32 m0, s2, 0x1d000
	s_nop 0
	global_load_lds_dwordx4 v134, s[30:31]
	ds_read_b128 v[242:245], v155 offset:21504
	ds_read_b128 v[246:249], v155 offset:22528
	ds_read_b128 v[250:253], v155 offset:23552
	s_add_i32 m0, s2, 0x1f000
	s_nop 0
	global_load_lds_dwordx4 v130, s[30:31]
	s_add_u32 s28, s28, 0x80
	s_addc_u32 s29, s29, 0
	s_waitcnt vmcnt(8) lgkmcnt(0)
	s_barrier
; #define PG8_STAGE(bufoff, gbase, voff) do { _Pragma("unroll") for (int _i = 0; _i < 2; ++_i) \
;         __builtin_amdgcn_global_load_lds((const unsigned*)((const char*)(gbase) + (voff)[_i]), (PG8_LAS unsigned*)(lds + (bufoff) + ldsw + _i * 8192), 16, 0, 0); } while (0)
; #define PG8_LDA(dst, b, h) do { _Pragma("unroll") for (int m = 0; m < 4; ++m) _Pragma("unroll") for (int k = 0; k < 2; ++k) dst[m][k] = *(const PG8_LAS bf16x8*)(lds + PG8_SA(b, h) + aoff + m * 2048 + k * 1024); } while (0)
; #define PG8_LDB(dst, b, h) do { _Pragma("unroll") for (int n = 0; n < 2; ++n) _Pragma("unroll") for (int k = 0; k < 2; ++k) dst[n][k] = *(const PG8_LAS bf16x8*)(lds + PG8_SB(b, h) + boff + n * 2048 + k * 1024); } while (0)
; #define PG8_MMA(ai, bj, At, Bt) do { __builtin_amdgcn_s_setprio(1); _Pragma("unroll") for (int m = 0; m < 4; ++m) _Pragma("unroll") for (int n = 0; n < 2; ++n) _Pragma("unroll") for (int k = 0; k < 2; ++k) \
;         acc[ai][bj][m][n] = __builtin_amdgcn_mfma_f32_16x16x32_bf16(Bt[n][k], At[m][k], acc[ai][bj][m][n], 0, 0, 0); __builtin_amdgcn_s_setprio(0); } while (0)
; #define PG8_WAIT_V(n) asm volatile("s_waitcnt vmcnt(" #n ")" ::: "memory")
; #define PG8_WAIT_L(n) asm volatile("s_waitcnt lgkmcnt(" #n ")" ::: "memory")
; #define PG8_BAR __builtin_amdgcn_s_barrier()
; #define PG8_SCHED __builtin_amdgcn_sched_barrier(0)
; template <class Epi, class Sched, bool ALIGN_EPI>
; __device__ __forceinline__ void gemm_phase(PG8_LAS unsigned char* lds, const Gemm g, const Sched& S, const Epi& E) {
;     ...
;             PG8_WAIT_V(8); PG8_WAIT_L(0); PG8_BAR; PG8_MMA(0, 0, At, B0); PG8_MMA(0, 1, At, B1); PG8_BAR; PG8_SCHED;
;             PG8_LDA(At, 0, 1); PG8_STAGE(PG8_SB(0, 0), b2, voffB); PG8_STAGE(PG8_SB(0, 1), b2 + hstepB, voffB); PG8_STAGE(PG8_SA(0, 0), a2, voffA);
;             PG8_WAIT_V(8); PG8_WAIT_L(0); PG8_BAR; PG8_MMA(1, 0, At, B0); PG8_MMA(1, 1, At, B1); PG8_BAR; PG8_SCHED;
;             PG8_LDB(B0, 1, 0); PG8_LDB(B1, 1, 1); PG8_SCHED; PG8_LDA(At, 1, 0); PG8_STAGE(PG8_SA(0, 1), a2 + hstepA, voffA);
;             PG8_WAIT_V(8); PG8_WAIT_L(0); PG8_BAR; PG8_MMA(0, 0, At, B0); PG8_MMA(0, 1, At, B1); PG8_BAR; PG8_SCHED;
	s_setprio 1
	v_mfma_f32_16x16x32_bf16 v[126:129], v[156:159], v[190:193], v[126:129]
	v_mfma_f32_16x16x32_bf16 v[126:129], v[160:163], v[194:197], v[126:129]
	v_mfma_f32_16x16x32_bf16 v[122:125], v[168:171], v[194:197], v[122:125]
	v_mfma_f32_16x16x32_bf16 v[122:125], v[164:167], v[190:193], v[122:125]
	v_mfma_f32_16x16x32_bf16 v[118:121], v[174:177], v[190:193], v[118:121]
	v_mfma_f32_16x16x32_bf16 v[118:121], v[178:181], v[194:197], v[118:121]
	v_mfma_f32_16x16x32_bf16 v[114:117], v[186:189], v[194:197], v[114:117]
	v_mfma_f32_16x16x32_bf16 v[114:117], v[182:185], v[190:193], v[114:117]
	v_mfma_f32_16x16x32_bf16 v[98:101], v[182:185], v[198:201], v[98:101]
	v_mfma_f32_16x16x32_bf16 v[98:101], v[186:189], v[202:205], v[98:101]
	v_mfma_f32_16x16x32_bf16 v[102:105], v[178:181], v[202:205], v[102:105]
	v_mfma_f32_16x16x32_bf16 v[102:105], v[174:177], v[198:201], v[102:105]
	v_mfma_f32_16x16x32_bf16 v[106:109], v[164:167], v[198:201], v[106:109]
	v_mfma_f32_16x16x32_bf16 v[106:109], v[168:171], v[202:205], v[106:109]
	v_mfma_f32_16x16x32_bf16 v[110:113], v[160:163], v[202:205], v[110:113]
	v_mfma_f32_16x16x32_bf16 v[110:113], v[156:159], v[198:201], v[110:113]
	v_mfma_f32_16x16x32_bf16 v[94:97], v[156:159], v[206:209], v[94:97]
	v_mfma_f32_16x16x32_bf16 v[94:97], v[160:163], v[210:213], v[94:97]
	v_mfma_f32_16x16x32_bf16 v[90:93], v[168:171], v[210:213], v[90:93]
	v_mfma_f32_16x16x32_bf16 v[90:93], v[164:167], v[206:209], v[90:93]
	v_mfma_f32_16x16x32_bf16 v[86:89], v[174:177], v[206:209], v[86:89]
	v_mfma_f32_16x16x32_bf16 v[86:89], v[178:181], v[210:213], v[86:89]
	v_mfma_f32_16x16x32_bf16 v[82:85], v[186:189], v[210:213], v[82:85]
	v_mfma_f32_16x16x32_bf16 v[82:85], v[182:185], v[206:209], v[82:85]
	v_mfma_f32_16x16x32_bf16 v[66:69], v[182:185], v[214:217], v[66:69]
	v_mfma_f32_16x16x32_bf16 v[66:69], v[186:189], v[218:221], v[66:69]
	v_mfma_f32_16x16x32_bf16 v[70:73], v[178:181], v[218:221], v[70:73]
	v_mfma_f32_16x16x32_bf16 v[70:73], v[174:177], v[214:217], v[70:73]
	v_mfma_f32_16x16x32_bf16 v[74:77], v[164:167], v[214:217], v[74:77]
	v_mfma_f32_16x16x32_bf16 v[74:77], v[168:171], v[218:221], v[74:77]
	v_mfma_f32_16x16x32_bf16 v[78:81], v[160:163], v[218:221], v[78:81]
	v_mfma_f32_16x16x32_bf16 v[78:81], v[156:159], v[214:217], v[78:81]
	v_mfma_f32_16x16x32_bf16 v[62:65], v[156:159], v[222:225], v[62:65]
	v_mfma_f32_16x16x32_bf16 v[62:65], v[160:163], v[226:229], v[62:65]
	v_mfma_f32_16x16x32_bf16 v[58:61], v[168:171], v[226:229], v[58:61]
	v_mfma_f32_16x16x32_bf16 v[58:61], v[164:167], v[222:225], v[58:61]
	v_mfma_f32_16x16x32_bf16 v[54:57], v[174:177], v[222:225], v[54:57]
	v_mfma_f32_16x16x32_bf16 v[54:57], v[178:181], v[226:229], v[54:57]
	v_mfma_f32_16x16x32_bf16 v[50:53], v[186:189], v[226:229], v[50:53]
	v_mfma_f32_16x16x32_bf16 v[50:53], v[182:185], v[222:225], v[50:53]
	v_mfma_f32_16x16x32_bf16 v[34:37], v[182:185], v[230:233], v[34:37]
	v_mfma_f32_16x16x32_bf16 v[34:37], v[186:189], v[234:237], v[34:37]
	v_mfma_f32_16x16x32_bf16 v[38:41], v[178:181], v[234:237], v[38:41]
	v_mfma_f32_16x16x32_bf16 v[38:41], v[174:177], v[230:233], v[38:41]
	v_mfma_f32_16x16x32_bf16 v[42:45], v[164:167], v[230:233], v[42:45]
	v_mfma_f32_16x16x32_bf16 v[42:45], v[168:171], v[234:237], v[42:45]
	v_mfma_f32_16x16x32_bf16 v[46:49], v[160:163], v[234:237], v[46:49]
	v_mfma_f32_16x16x32_bf16 v[46:49], v[156:159], v[230:233], v[46:49]
	v_mfma_f32_16x16x32_bf16 v[30:33], v[156:159], v[238:241], v[30:33]
	v_mfma_f32_16x16x32_bf16 v[30:33], v[160:163], v[242:245], v[30:33]
	v_mfma_f32_16x16x32_bf16 v[26:29], v[168:171], v[242:245], v[26:29]
	v_mfma_f32_16x16x32_bf16 v[26:29], v[164:167], v[238:241], v[26:29]
	v_mfma_f32_16x16x32_bf16 v[22:25], v[174:177], v[238:241], v[22:25]
	v_mfma_f32_16x16x32_bf16 v[22:25], v[178:181], v[242:245], v[22:25]
	v_mfma_f32_16x16x32_bf16 v[18:21], v[186:189], v[242:245], v[18:21]
	v_mfma_f32_16x16x32_bf16 v[18:21], v[182:185], v[238:241], v[18:21]
	v_mfma_f32_16x16x32_bf16 v[2:5], v[182:185], v[246:249], v[2:5]
	v_mfma_f32_16x16x32_bf16 v[2:5], v[186:189], v[250:253], v[2:5]
	v_mfma_f32_16x16x32_bf16 v[6:9], v[178:181], v[250:253], v[6:9]
	v_mfma_f32_16x16x32_bf16 v[6:9], v[174:177], v[246:249], v[6:9]
	v_mfma_f32_16x16x32_bf16 v[10:13], v[164:167], v[246:249], v[10:13]
	v_mfma_f32_16x16x32_bf16 v[10:13], v[168:171], v[250:253], v[10:13]
	v_mfma_f32_16x16x32_bf16 v[14:17], v[160:163], v[250:253], v[14:17]
	v_mfma_f32_16x16x32_bf16 v[14:17], v[156:159], v[246:249], v[14:17]
	s_setprio 0
	s_waitcnt vmcnt(0)
	s_barrier
	ds_read_b128 v[190:193], v155 offset:32768
	ds_read_b128 v[194:197], v155 offset:33792
	ds_read_b128 v[198:201], v155 offset:34816
	s_cmp_eq_u32 s49, 15
	s_cselect_b32 s28, s50, s28
	s_cselect_b32 s29, s51, s29
	s_add_i32 m0, s2, 0x10000
	s_nop 0
	global_load_lds_dwordx4 v134, s[28:29]
	ds_read_b128 v[202:205], v155 offset:35840
	ds_read_b128 v[206:209], v155 offset:36864
	ds_read_b128 v[210:213], v155 offset:37888
	s_add_i32 m0, s2, 0x12000
	s_nop 0
	global_load_lds_dwordx4 v130, s[28:29]
	ds_read_b128 v[214:217], v155 offset:38912
	ds_read_b128 v[218:221], v155 offset:39936
	ds_read_b128 v[156:159], v153 offset:32768
	s_add_u32 s30, s28, 0x20000
	s_addc_u32 s31, s29, 0
	s_add_i32 m0, s2, 0x11000
	s_nop 0
	global_load_lds_dwordx4 v134, s[30:31]
	ds_read_b128 v[160:163], v153 offset:33792
	ds_read_b128 v[164:167], v153 offset:34816
	ds_read_b128 v[168:171], v153 offset:35840
	s_add_i32 m0, s2, 0x13000
	s_nop 0
	global_load_lds_dwordx4 v130, s[30:31]
	ds_read_b128 v[174:177], v153 offset:49152
	ds_read_b128 v[178:181], v153 offset:50176
	ds_read_b128 v[182:185], v153 offset:51200
	s_add_u32 s30, s28, 0x80000
	s_addc_u32 s31, s29, 0
	s_add_i32 m0, s2, 0x14000
	s_nop 0
	global_load_lds_dwordx4 v134, s[30:31]
	ds_read_b128 v[186:189], v153 offset:52224
	ds_read_b128 v[222:225], v155 offset:49152
	ds_read_b128 v[226:229], v155 offset:50176
	s_add_i32 m0, s2, 0x16000
	s_nop 0
	global_load_lds_dwordx4 v130, s[30:31]
	ds_read_b128 v[230:233], v155 offset:51200
	ds_read_b128 v[234:237], v155 offset:52224
	ds_read_b128 v[238:241], v155 offset:53248
	s_add_u32 s30, s28, 0xa0000
	s_addc_u32 s31, s29, 0
	s_add_i32 m0, s2, 0x15000
	s_nop 0
	global_load_lds_dwordx4 v134, s[30:31]
	ds_read_b128 v[242:245], v155 offset:54272
	ds_read_b128 v[246:249], v155 offset:55296
	ds_read_b128 v[250:253], v155 offset:56320
	s_add_i32 m0, s2, 0x17000
	s_nop 0
	global_load_lds_dwordx4 v130, s[30:31]
	s_add_u32 s28, s28, 0x80
	s_addc_u32 s29, s29, 0
	s_waitcnt vmcnt(8) lgkmcnt(0)
	s_barrier
; #define PG8_STAGE(bufoff, gbase, voff) do { _Pragma("unroll") for (int _i = 0; _i < 2; ++_i) \
;         __builtin_amdgcn_global_load_lds((const unsigned*)((const char*)(gbase) + (voff)[_i]), (PG8_LAS unsigned*)(lds + (bufoff) + ldsw + _i * 8192), 16, 0, 0); } while (0)
; #define PG8_LDA(dst, b, h) do { _Pragma("unroll") for (int m = 0; m < 4; ++m) _Pragma("unroll") for (int k = 0; k < 2; ++k) dst[m][k] = *(const PG8_LAS bf16x8*)(lds + PG8_SA(b, h) + aoff + m * 2048 + k * 1024); } while (0)
; #define PG8_MMA(ai, bj, At, Bt) do { __builtin_amdgcn_s_setprio(1); _Pragma("unroll") for (int m = 0; m < 4; ++m) _Pragma("unroll") for (int n = 0; n < 2; ++n) _Pragma("unroll") for (int k = 0; k < 2; ++k) \
;         acc[ai][bj][m][n] = __builtin_amdgcn_mfma_f32_16x16x32_bf16(Bt[n][k], At[m][k], acc[ai][bj][m][n], 0, 0, 0); __builtin_amdgcn_s_setprio(0); } while (0)
; #define PG8_WAIT_V(n) asm volatile("s_waitcnt vmcnt(" #n ")" ::: "memory")
; #define PG8_WAIT_L(n) asm volatile("s_waitcnt lgkmcnt(" #n ")" ::: "memory")
; #define PG8_BAR __builtin_amdgcn_s_barrier()
; #define PG8_SCHED __builtin_amdgcn_sched_barrier(0)
; template <class Epi, class Sched, bool ALIGN_EPI>
; __device__ __forceinline__ void gemm_phase(PG8_LAS unsigned char* lds, const Gemm g, const Sched& S, const Epi& E) {
;     ...
;             PG8_WAIT_V(8); PG8_WAIT_L(0); PG8_BAR; PG8_MMA(0, 0, At, B0); PG8_MMA(0, 1, At, B1); PG8_BAR; PG8_SCHED;
;             PG8_LDA(At, 1, 1); PG8_STAGE(PG8_SB(1, 0), b3, voffB); PG8_STAGE(PG8_SB(1, 1), b3 + hstepB, voffB); PG8_STAGE(PG8_SA(1, 0), a3, voffA);
;             PG8_WAIT_V(8); PG8_WAIT_L(0); PG8_BAR; PG8_MMA(1, 0, At, B0); PG8_MMA(1, 1, At, B1); PG8_BAR; PG8_SCHED;
;         }
;         if constexpr (ALIGN_EPI) { if (wr == 0) PG8_BAR; }
	s_setprio 1
	v_mfma_f32_16x16x32_bf16 v[126:129], v[156:159], v[190:193], v[126:129]
	v_mfma_f32_16x16x32_bf16 v[126:129], v[160:163], v[194:197], v[126:129]
	v_mfma_f32_16x16x32_bf16 v[122:125], v[168:171], v[194:197], v[122:125]
	v_mfma_f32_16x16x32_bf16 v[122:125], v[164:167], v[190:193], v[122:125]
	v_mfma_f32_16x16x32_bf16 v[118:121], v[174:177], v[190:193], v[118:121]
	v_mfma_f32_16x16x32_bf16 v[118:121], v[178:181], v[194:197], v[118:121]
	v_mfma_f32_16x16x32_bf16 v[114:117], v[186:189], v[194:197], v[114:117]
	v_mfma_f32_16x16x32_bf16 v[114:117], v[182:185], v[190:193], v[114:117]
	v_mfma_f32_16x16x32_bf16 v[98:101], v[182:185], v[198:201], v[98:101]
	v_mfma_f32_16x16x32_bf16 v[98:101], v[186:189], v[202:205], v[98:101]
	v_mfma_f32_16x16x32_bf16 v[102:105], v[178:181], v[202:205], v[102:105]
	v_mfma_f32_16x16x32_bf16 v[102:105], v[174:177], v[198:201], v[102:105]
	v_mfma_f32_16x16x32_bf16 v[106:109], v[164:167], v[198:201], v[106:109]
	v_mfma_f32_16x16x32_bf16 v[106:109], v[168:171], v[202:205], v[106:109]
	v_mfma_f32_16x16x32_bf16 v[110:113], v[160:163], v[202:205], v[110:113]
	v_mfma_f32_16x16x32_bf16 v[110:113], v[156:159], v[198:201], v[110:113]
	v_mfma_f32_16x16x32_bf16 v[94:97], v[156:159], v[206:209], v[94:97]
	v_mfma_f32_16x16x32_bf16 v[94:97], v[160:163], v[210:213], v[94:97]
	v_mfma_f32_16x16x32_bf16 v[90:93], v[168:171], v[210:213], v[90:93]
	v_mfma_f32_16x16x32_bf16 v[90:93], v[164:167], v[206:209], v[90:93]
	v_mfma_f32_16x16x32_bf16 v[86:89], v[174:177], v[206:209], v[86:89]
	v_mfma_f32_16x16x32_bf16 v[86:89], v[178:181], v[210:213], v[86:89]
	v_mfma_f32_16x16x32_bf16 v[82:85], v[186:189], v[210:213], v[82:85]
	v_mfma_f32_16x16x32_bf16 v[82:85], v[182:185], v[206:209], v[82:85]
	v_mfma_f32_16x16x32_bf16 v[66:69], v[182:185], v[214:217], v[66:69]
	v_mfma_f32_16x16x32_bf16 v[66:69], v[186:189], v[218:221], v[66:69]
	v_mfma_f32_16x16x32_bf16 v[70:73], v[178:181], v[218:221], v[70:73]
	v_mfma_f32_16x16x32_bf16 v[70:73], v[174:177], v[214:217], v[70:73]
	v_mfma_f32_16x16x32_bf16 v[74:77], v[164:167], v[214:217], v[74:77]
	v_mfma_f32_16x16x32_bf16 v[74:77], v[168:171], v[218:221], v[74:77]
	v_mfma_f32_16x16x32_bf16 v[78:81], v[160:163], v[218:221], v[78:81]
	v_mfma_f32_16x16x32_bf16 v[78:81], v[156:159], v[214:217], v[78:81]
	v_mfma_f32_16x16x32_bf16 v[62:65], v[156:159], v[222:225], v[62:65]
	v_mfma_f32_16x16x32_bf16 v[62:65], v[160:163], v[226:229], v[62:65]
	v_mfma_f32_16x16x32_bf16 v[58:61], v[168:171], v[226:229], v[58:61]
	v_mfma_f32_16x16x32_bf16 v[58:61], v[164:167], v[222:225], v[58:61]
	v_mfma_f32_16x16x32_bf16 v[54:57], v[174:177], v[222:225], v[54:57]
	v_mfma_f32_16x16x32_bf16 v[54:57], v[178:181], v[226:229], v[54:57]
	v_mfma_f32_16x16x32_bf16 v[50:53], v[186:189], v[226:229], v[50:53]
	v_mfma_f32_16x16x32_bf16 v[50:53], v[182:185], v[222:225], v[50:53]
	v_mfma_f32_16x16x32_bf16 v[34:37], v[182:185], v[230:233], v[34:37]
	v_mfma_f32_16x16x32_bf16 v[34:37], v[186:189], v[234:237], v[34:37]
	v_mfma_f32_16x16x32_bf16 v[38:41], v[178:181], v[234:237], v[38:41]
	v_mfma_f32_16x16x32_bf16 v[38:41], v[174:177], v[230:233], v[38:41]
	v_mfma_f32_16x16x32_bf16 v[42:45], v[164:167], v[230:233], v[42:45]
	v_mfma_f32_16x16x32_bf16 v[42:45], v[168:171], v[234:237], v[42:45]
	v_mfma_f32_16x16x32_bf16 v[46:49], v[160:163], v[234:237], v[46:49]
	v_mfma_f32_16x16x32_bf16 v[46:49], v[156:159], v[230:233], v[46:49]
	v_mfma_f32_16x16x32_bf16 v[30:33], v[156:159], v[238:241], v[30:33]
	v_mfma_f32_16x16x32_bf16 v[30:33], v[160:163], v[242:245], v[30:33]
	v_mfma_f32_16x16x32_bf16 v[26:29], v[168:171], v[242:245], v[26:29]
	v_mfma_f32_16x16x32_bf16 v[26:29], v[164:167], v[238:241], v[26:29]
	v_mfma_f32_16x16x32_bf16 v[22:25], v[174:177], v[238:241], v[22:25]
	v_mfma_f32_16x16x32_bf16 v[22:25], v[178:181], v[242:245], v[22:25]
	v_mfma_f32_16x16x32_bf16 v[18:21], v[186:189], v[242:245], v[18:21]
	v_mfma_f32_16x16x32_bf16 v[18:21], v[182:185], v[238:241], v[18:21]
	v_mfma_f32_16x16x32_bf16 v[2:5], v[182:185], v[246:249], v[2:5]
	v_mfma_f32_16x16x32_bf16 v[2:5], v[186:189], v[250:253], v[2:5]
	v_mfma_f32_16x16x32_bf16 v[6:9], v[178:181], v[250:253], v[6:9]
	v_mfma_f32_16x16x32_bf16 v[6:9], v[174:177], v[246:249], v[6:9]
	v_mfma_f32_16x16x32_bf16 v[10:13], v[164:167], v[246:249], v[10:13]
	v_mfma_f32_16x16x32_bf16 v[10:13], v[168:171], v[250:253], v[10:13]
	v_mfma_f32_16x16x32_bf16 v[14:17], v[160:163], v[250:253], v[14:17]
	v_mfma_f32_16x16x32_bf16 v[14:17], v[156:159], v[246:249], v[14:17]
	s_setprio 0
	s_waitcnt vmcnt(0)
	s_barrier
	s_add_i32 s49, s49, 1
	s_cmp_lt_u32 s49, 16
	s_cbranch_scc1 .Lp8k_A_loop
	ds_read_b128 v[190:193], v155 offset:0
	ds_read_b128 v[194:197], v155 offset:1024
	ds_read_b128 v[198:201], v155 offset:2048
	s_add_i32 m0, s2, 0x18000
	s_nop 0
	global_load_lds_dwordx4 v134, s[28:29]
	ds_read_b128 v[202:205], v155 offset:3072
	ds_read_b128 v[206:209], v155 offset:4096
	ds_read_b128 v[210:213], v155 offset:5120
	s_add_i32 m0, s2, 0x1a000
	s_nop 0
	global_load_lds_dwordx4 v130, s[28:29]
	ds_read_b128 v[214:217], v155 offset:6144
	ds_read_b128 v[218:221], v155 offset:7168
	ds_read_b128 v[164:167], v153 offset:2048
	s_add_u32 s30, s28, 0x20000
	s_addc_u32 s31, s29, 0
	s_add_i32 m0, s2, 0x19000
	s_nop 0
	global_load_lds_dwordx4 v134, s[30:31]
	ds_read_b128 v[168:171], v153 offset:3072
	ds_read_b128 v[174:177], v153 offset:16384
	ds_read_b128 v[178:181], v153 offset:17408
	s_add_i32 m0, s2, 0x1b000
	s_nop 0
	global_load_lds_dwordx4 v130, s[30:31]
	ds_read_b128 v[182:185], v153 offset:18432
	ds_read_b128 v[186:189], v153 offset:19456
	ds_read_b128 v[222:225], v155 offset:16384
	s_add_u32 s30, s28, 0x80000
	s_addc_u32 s31, s29, 0
	s_add_i32 m0, s2, 0x1c000
	s_nop 0
	global_load_lds_dwordx4 v134, s[30:31]
	ds_read_b128 v[226:229], v155 offset:17408
	ds_read_b128 v[230:233], v155 offset:18432
	ds_read_b128 v[234:237], v155 offset:19456
	s_add_i32 m0, s2, 0x1e000
	s_nop 0
	global_load_lds_dwordx4 v130, s[30:31]
	ds_read_b128 v[238:241], v155 offset:20480
	ds_read_b128 v[242:245], v155 offset:21504
	ds_read_b128 v[246:249], v155 offset:22528
	s_add_u32 s30, s28, 0xa0000
	s_addc_u32 s31, s29, 0
	s_add_i32 m0, s2, 0x1d000
	s_nop 0
	global_load_lds_dwordx4 v134, s[30:31]
	ds_read_b128 v[250:253], v155 offset:23552
	s_add_i32 m0, s2, 0x1f000
	s_nop 0
	global_load_lds_dwordx4 v130, s[30:31]
	s_add_u32 s28, s28, 0x80
	s_addc_u32 s29, s29, 0
	s_branch .Lp8k_done

; #define PG8_STAGE(bufoff, gbase, voff) do { _Pragma("unroll") for (int _i = 0; _i < 2; ++_i) \
;         __builtin_amdgcn_global_load_lds((const unsigned*)((const char*)(gbase) + (voff)[_i]), (PG8_LAS unsigned*)(lds + (bufoff) + ldsw + _i * 8192), 16, 0, 0); } while (0)
; #define PG8_LDA(dst, b, h) do { _Pragma("unroll") for (int m = 0; m < 4; ++m) _Pragma("unroll") for (int k = 0; k < 2; ++k) dst[m][k] = *(const PG8_LAS bf16x8*)(lds + PG8_SA(b, h) + aoff + m * 2048 + k * 1024); } while (0)
; #define PG8_LDB(dst, b, h) do { _Pragma("unroll") for (int n = 0; n < 2; ++n) _Pragma("unroll") for (int k = 0; k < 2; ++k) dst[n][k] = *(const PG8_LAS bf16x8*)(lds + PG8_SB(b, h) + boff + n * 2048 + k * 1024); } while (0)
; #define PG8_MMA(ai, bj, At, Bt) do { __builtin_amdgcn_s_setprio(1); _Pragma("unroll") for (int m = 0; m < 4; ++m) _Pragma("unroll") for (int n = 0; n < 2; ++n) _Pragma("unroll") for (int k = 0; k < 2; ++k) \
;         acc[ai][bj][m][n] = __builtin_amdgcn_mfma_f32_16x16x32_bf16(Bt[n][k], At[m][k], acc[ai][bj][m][n], 0, 0, 0); __builtin_amdgcn_s_setprio(0); } while (0)
; #define PG8_WAIT_V(n) asm volatile("s_waitcnt vmcnt(" #n ")" ::: "memory")
; #define PG8_WAIT_L(n) asm volatile("s_waitcnt lgkmcnt(" #n ")" ::: "memory")
; #define PG8_BAR __builtin_amdgcn_s_barrier()
; #define PG8_SCHED __builtin_amdgcn_sched_barrier(0)
; template <class Epi, class Sched, bool ALIGN_EPI>
; __device__ __forceinline__ void gemm_phase(PG8_LAS unsigned char* lds, const Gemm g, const Sched& S, const Epi& E) {
;     ...
;             PG8_LDB(B0, 0, 0); PG8_LDB(B1, 0, 1); PG8_SCHED; PG8_LDA(At, 0, 0); PG8_STAGE(PG8_SA(1, 1), a1 + hstepA, voffA);
;             PG8_WAIT_V(8); PG8_WAIT_L(0); PG8_BAR; PG8_MMA(0, 0, At, B0); PG8_MMA(0, 1, At, B1); PG8_BAR; PG8_SCHED;
;             PG8_LDA(At, 0, 1); PG8_STAGE(PG8_SB(0, 0), b2, voffB); PG8_STAGE(PG8_SB(0, 1), b2 + hstepB, voffB); PG8_STAGE(PG8_SA(0, 0), a2, voffA);
;             PG8_WAIT_V(8); PG8_WAIT_L(0); PG8_BAR; PG8_MMA(1, 0, At, B0); PG8_MMA(1, 1, At, B1); PG8_BAR; PG8_SCHED;
.Lp8k_B_nobar:
	ds_read_b128 v[190:193], v155 offset:0
	ds_read_b128 v[194:197], v155 offset:1024
	ds_read_b128 v[198:201], v155 offset:2048
	s_add_i32 m0, s2, 0xa000
	s_nop 0
	global_load_lds_dwordx4 v132, s[28:29]
	ds_read_b128 v[202:205], v155 offset:3072
	ds_read_b128 v[206:209], v155 offset:4096
	ds_read_b128 v[210:213], v155 offset:5120
	s_add_u32 s30, s28, 0x20000
	s_addc_u32 s31, s29, 0
	s_add_i32 m0, s2, 0xb000
	s_nop 0
	global_load_lds_dwordx4 v132, s[30:31]
	ds_read_b128 v[214:217], v155 offset:6144
	ds_read_b128 v[218:221], v155 offset:7168
	ds_read_b128 v[156:159], v153 offset:0
	s_add_u32 s30, s28, 0x80000
	s_addc_u32 s31, s29, 0
	s_add_i32 m0, s2, 0xe000
	s_nop 0
	global_load_lds_dwordx4 v132, s[30:31]
	ds_read_b128 v[160:163], v153 offset:1024
	ds_read_b128 v[164:167], v153 offset:2048
	ds_read_b128 v[168:171], v153 offset:3072
	s_add_u32 s30, s28, 0xa0000
	s_addc_u32 s31, s29, 0
	s_add_i32 m0, s2, 0xf000
	s_nop 0
	global_load_lds_dwordx4 v132, s[30:31]
	ds_read_b128 v[174:177], v153 offset:16384
	ds_read_b128 v[178:181], v153 offset:17408
	ds_read_b128 v[182:185], v153 offset:18432
	s_add_u32 s34, s28, 0x80
	s_addc_u32 s35, s29, 0
	s_cmp_eq_u32 s49, 15
	s_cselect_b32 s34, s50, s34
	s_cselect_b32 s35, s51, s35
	s_add_i32 m0, s2, 0x0
	s_nop 0
	global_load_lds_dwordx4 v136, s[34:35]
	ds_read_b128 v[186:189], v153 offset:19456
	ds_read_b128 v[222:225], v155 offset:16384
	ds_read_b128 v[226:229], v155 offset:17408
	s_add_u32 s30, s34, 0x20000
	s_addc_u32 s31, s35, 0
	s_add_i32 m0, s2, 0x1000
	s_nop 0
	global_load_lds_dwordx4 v136, s[30:31]
	ds_read_b128 v[230:233], v155 offset:18432
	ds_read_b128 v[234:237], v155 offset:19456
	ds_read_b128 v[238:241], v155 offset:20480
	s_add_u32 s30, s34, 0x80000
	s_addc_u32 s31, s35, 0
	s_add_i32 m0, s2, 0x4000
	s_nop 0
	global_load_lds_dwordx4 v136, s[30:31]
	ds_read_b128 v[242:245], v155 offset:21504
	ds_read_b128 v[246:249], v155 offset:22528
	ds_read_b128 v[250:253], v155 offset:23552
	s_add_u32 s30, s34, 0xa0000
	s_addc_u32 s31, s35, 0
	s_add_i32 m0, s2, 0x5000
	s_nop 0
	global_load_lds_dwordx4 v136, s[30:31]
	s_add_u32 s28, s28, 0x80
	s_addc_u32 s29, s29, 0
	s_waitcnt vmcnt(8) lgkmcnt(0)
	s_barrier
	s_setprio 1
	v_mfma_f32_16x16x32_bf16 v[126:129], v[156:159], v[190:193], 0
	v_mfma_f32_16x16x32_bf16 v[126:129], v[160:163], v[194:197], v[126:129]
	v_mfma_f32_16x16x32_bf16 v[122:125], v[168:171], v[194:197], 0
	v_mfma_f32_16x16x32_bf16 v[122:125], v[164:167], v[190:193], v[122:125]
	v_mfma_f32_16x16x32_bf16 v[118:121], v[174:177], v[190:193], 0
	v_mfma_f32_16x16x32_bf16 v[118:121], v[178:181], v[194:197], v[118:121]
	v_mfma_f32_16x16x32_bf16 v[114:117], v[186:189], v[194:197], 0
	v_mfma_f32_16x16x32_bf16 v[114:117], v[182:185], v[190:193], v[114:117]
	v_mfma_f32_16x16x32_bf16 v[98:101], v[182:185], v[198:201], 0
	v_mfma_f32_16x16x32_bf16 v[98:101], v[186:189], v[202:205], v[98:101]
	v_mfma_f32_16x16x32_bf16 v[102:105], v[178:181], v[202:205], 0
	v_mfma_f32_16x16x32_bf16 v[102:105], v[174:177], v[198:201], v[102:105]
	v_mfma_f32_16x16x32_bf16 v[106:109], v[164:167], v[198:201], 0
	v_mfma_f32_16x16x32_bf16 v[106:109], v[168:171], v[202:205], v[106:109]
	v_mfma_f32_16x16x32_bf16 v[110:113], v[160:163], v[202:205], 0
	v_mfma_f32_16x16x32_bf16 v[110:113], v[156:159], v[198:201], v[110:113]
	v_mfma_f32_16x16x32_bf16 v[94:97], v[156:159], v[206:209], 0
	v_mfma_f32_16x16x32_bf16 v[94:97], v[160:163], v[210:213], v[94:97]
	v_mfma_f32_16x16x32_bf16 v[90:93], v[168:171], v[210:213], 0
	v_mfma_f32_16x16x32_bf16 v[90:93], v[164:167], v[206:209], v[90:93]
	v_mfma_f32_16x16x32_bf16 v[86:89], v[174:177], v[206:209], 0
	v_mfma_f32_16x16x32_bf16 v[86:89], v[178:181], v[210:213], v[86:89]
	v_mfma_f32_16x16x32_bf16 v[82:85], v[186:189], v[210:213], 0
	v_mfma_f32_16x16x32_bf16 v[82:85], v[182:185], v[206:209], v[82:85]
	v_mfma_f32_16x16x32_bf16 v[66:69], v[182:185], v[214:217], 0
	v_mfma_f32_16x16x32_bf16 v[66:69], v[186:189], v[218:221], v[66:69]
	v_mfma_f32_16x16x32_bf16 v[70:73], v[178:181], v[218:221], 0
	v_mfma_f32_16x16x32_bf16 v[70:73], v[174:177], v[214:217], v[70:73]
	v_mfma_f32_16x16x32_bf16 v[74:77], v[164:167], v[214:217], 0
	v_mfma_f32_16x16x32_bf16 v[74:77], v[168:171], v[218:221], v[74:77]
	v_mfma_f32_16x16x32_bf16 v[78:81], v[160:163], v[218:221], 0
	v_mfma_f32_16x16x32_bf16 v[78:81], v[156:159], v[214:217], v[78:81]
	v_mfma_f32_16x16x32_bf16 v[62:65], v[156:159], v[222:225], 0
	v_mfma_f32_16x16x32_bf16 v[62:65], v[160:163], v[226:229], v[62:65]
	v_mfma_f32_16x16x32_bf16 v[58:61], v[168:171], v[226:229], 0
	v_mfma_f32_16x16x32_bf16 v[58:61], v[164:167], v[222:225], v[58:61]
	v_mfma_f32_16x16x32_bf16 v[54:57], v[174:177], v[222:225], 0
	v_mfma_f32_16x16x32_bf16 v[54:57], v[178:181], v[226:229], v[54:57]
	v_mfma_f32_16x16x32_bf16 v[50:53], v[186:189], v[226:229], 0
	v_mfma_f32_16x16x32_bf16 v[50:53], v[182:185], v[222:225], v[50:53]
	v_mfma_f32_16x16x32_bf16 v[34:37], v[182:185], v[230:233], 0
	v_mfma_f32_16x16x32_bf16 v[34:37], v[186:189], v[234:237], v[34:37]
	v_mfma_f32_16x16x32_bf16 v[38:41], v[178:181], v[234:237], 0
	v_mfma_f32_16x16x32_bf16 v[38:41], v[174:177], v[230:233], v[38:41]
	v_mfma_f32_16x16x32_bf16 v[42:45], v[164:167], v[230:233], 0
	v_mfma_f32_16x16x32_bf16 v[42:45], v[168:171], v[234:237], v[42:45]
	v_mfma_f32_16x16x32_bf16 v[46:49], v[160:163], v[234:237], 0
	v_mfma_f32_16x16x32_bf16 v[46:49], v[156:159], v[230:233], v[46:49]
	v_mfma_f32_16x16x32_bf16 v[30:33], v[156:159], v[238:241], 0
	v_mfma_f32_16x16x32_bf16 v[30:33], v[160:163], v[242:245], v[30:33]
	v_mfma_f32_16x16x32_bf16 v[26:29], v[168:171], v[242:245], 0
	v_mfma_f32_16x16x32_bf16 v[26:29], v[164:167], v[238:241], v[26:29]
	v_mfma_f32_16x16x32_bf16 v[22:25], v[174:177], v[238:241], 0
	v_mfma_f32_16x16x32_bf16 v[22:25], v[178:181], v[242:245], v[22:25]
	v_mfma_f32_16x16x32_bf16 v[18:21], v[186:189], v[242:245], 0
	v_mfma_f32_16x16x32_bf16 v[18:21], v[182:185], v[238:241], v[18:21]
	v_mfma_f32_16x16x32_bf16 v[2:5], v[182:185], v[246:249], 0
	v_mfma_f32_16x16x32_bf16 v[2:5], v[186:189], v[250:253], v[2:5]
	v_mfma_f32_16x16x32_bf16 v[6:9], v[178:181], v[250:253], 0
	v_mfma_f32_16x16x32_bf16 v[6:9], v[174:177], v[246:249], v[6:9]
	v_mfma_f32_16x16x32_bf16 v[10:13], v[164:167], v[246:249], 0
	v_mfma_f32_16x16x32_bf16 v[10:13], v[168:171], v[250:253], v[10:13]
	v_mfma_f32_16x16x32_bf16 v[14:17], v[160:163], v[250:253], 0
	v_mfma_f32_16x16x32_bf16 v[14:17], v[156:159], v[246:249], v[14:17]
	s_setprio 0
	s_waitcnt vmcnt(0)
	s_barrier
; #define PG8_STAGE(bufoff, gbase, voff) do { _Pragma("unroll") for (int _i = 0; _i < 2; ++_i) \
;         __builtin_amdgcn_global_load_lds((const unsigned*)((const char*)(gbase) + (voff)[_i]), (PG8_LAS unsigned*)(lds + (bufoff) + ldsw + _i * 8192), 16, 0, 0); } while (0)
; #define PG8_LDA(dst, b, h) do { _Pragma("unroll") for (int m = 0; m < 4; ++m) _Pragma("unroll") for (int k = 0; k < 2; ++k) dst[m][k] = *(const PG8_LAS bf16x8*)(lds + PG8_SA(b, h) + aoff + m * 2048 + k * 1024); } while (0)
; #define PG8_LDB(dst, b, h) do { _Pragma("unroll") for (int n = 0; n < 2; ++n) _Pragma("unroll") for (int k = 0; k < 2; ++k) dst[n][k] = *(const PG8_LAS bf16x8*)(lds + PG8_SB(b, h) + boff + n * 2048 + k * 1024); } while (0)
; #define PG8_MMA(ai, bj, At, Bt) do { __builtin_amdgcn_s_setprio(1); _Pragma("unroll") for (int m = 0; m < 4; ++m) _Pragma("unroll") for (int n = 0; n < 2; ++n) _Pragma("unroll") for (int k = 0; k < 2; ++k) \
;         acc[ai][bj][m][n] = __builtin_amdgcn_mfma_f32_16x16x32_bf16(Bt[n][k], At[m][k], acc[ai][bj][m][n], 0, 0, 0); __builtin_amdgcn_s_setprio(0); } while (0)
; #define PG8_WAIT_V(n) asm volatile("s_waitcnt vmcnt(" #n ")" ::: "memory")
; #define PG8_WAIT_L(n) asm volatile("s_waitcnt lgkmcnt(" #n ")" ::: "memory")
; #define PG8_BAR __builtin_amdgcn_s_barrier()
; #define PG8_SCHED __builtin_amdgcn_sched_barrier(0)
; template <class Epi, class Sched, bool ALIGN_EPI>
; __device__ __forceinline__ void gemm_phase(PG8_LAS unsigned char* lds, const Gemm g, const Sched& S, const Epi& E) {
;     ...
;             PG8_LDB(B0, 1, 0); PG8_LDB(B1, 1, 1); PG8_SCHED; PG8_LDA(At, 1, 0); PG8_STAGE(PG8_SA(0, 1), a2 + hstepA, voffA);
;             PG8_WAIT_V(8); PG8_WAIT_L(0); PG8_BAR; PG8_MMA(0, 0, At, B0); PG8_MMA(0, 1, At, B1); PG8_BAR; PG8_SCHED;
;             PG8_LDA(At, 1, 1); PG8_STAGE(PG8_SB(1, 0), b3, voffB); PG8_STAGE(PG8_SB(1, 1), b3 + hstepB, voffB); PG8_STAGE(PG8_SA(1, 0), a3, voffA);
;             PG8_WAIT_V(8); PG8_WAIT_L(0); PG8_BAR; PG8_MMA(1, 0, At, B0); PG8_MMA(1, 1, At, B1); PG8_BAR; PG8_SCHED;
	ds_read_b128 v[190:193], v155 offset:32768
	ds_read_b128 v[194:197], v155 offset:33792
	ds_read_b128 v[198:201], v155 offset:34816
	s_cmp_eq_u32 s49, 15
	s_cselect_b32 s28, s50, s28
	s_cselect_b32 s29, s51, s29
	s_add_i32 m0, s2, 0x2000
	s_nop 0
	global_load_lds_dwordx4 v132, s[28:29]
	ds_read_b128 v[202:205], v155 offset:35840
	ds_read_b128 v[206:209], v155 offset:36864
	ds_read_b128 v[210:213], v155 offset:37888
	s_add_u32 s30, s28, 0x20000
	s_addc_u32 s31, s29, 0
	s_add_i32 m0, s2, 0x3000
	s_nop 0
	global_load_lds_dwordx4 v132, s[30:31]
	ds_read_b128 v[214:217], v155 offset:38912
	ds_read_b128 v[218:221], v155 offset:39936
	ds_read_b128 v[156:159], v153 offset:32768
	s_add_u32 s30, s28, 0x80000
	s_addc_u32 s31, s29, 0
	s_add_i32 m0, s2, 0x6000
	s_nop 0
	global_load_lds_dwordx4 v132, s[30:31]
	ds_read_b128 v[160:163], v153 offset:33792
	ds_read_b128 v[164:167], v153 offset:34816
	ds_read_b128 v[168:171], v153 offset:35840
	s_add_u32 s30, s28, 0xa0000
	s_addc_u32 s31, s29, 0
	s_add_i32 m0, s2, 0x7000
	s_nop 0
	global_load_lds_dwordx4 v132, s[30:31]
	ds_read_b128 v[174:177], v153 offset:49152
	ds_read_b128 v[178:181], v153 offset:50176
	ds_read_b128 v[182:185], v153 offset:51200
	s_add_u32 s34, s28, 0x80
	s_addc_u32 s35, s29, 0
	s_add_i32 m0, s2, 0x8000
	s_nop 0
	global_load_lds_dwordx4 v136, s[34:35]
	ds_read_b128 v[186:189], v153 offset:52224
	ds_read_b128 v[222:225], v155 offset:49152
	ds_read_b128 v[226:229], v155 offset:50176
	s_add_u32 s30, s34, 0x20000
	s_addc_u32 s31, s35, 0
	s_add_i32 m0, s2, 0x9000
	s_nop 0
	global_load_lds_dwordx4 v136, s[30:31]
	ds_read_b128 v[230:233], v155 offset:51200
	ds_read_b128 v[234:237], v155 offset:52224
	ds_read_b128 v[238:241], v155 offset:53248
	s_add_u32 s30, s34, 0x80000
	s_addc_u32 s31, s35, 0
	s_add_i32 m0, s2, 0xc000
	s_nop 0
	global_load_lds_dwordx4 v136, s[30:31]
	ds_read_b128 v[242:245], v155 offset:54272
	ds_read_b128 v[246:249], v155 offset:55296
	ds_read_b128 v[250:253], v155 offset:56320
	s_add_u32 s30, s34, 0xa0000
	s_addc_u32 s31, s35, 0
	s_add_i32 m0, s2, 0xd000
	s_nop 0
	global_load_lds_dwordx4 v136, s[30:31]
	s_add_u32 s28, s28, 0x80
	s_addc_u32 s29, s29, 0
	s_waitcnt vmcnt(8) lgkmcnt(0)
	s_barrier
	s_setprio 1
	v_mfma_f32_16x16x32_bf16 v[126:129], v[156:159], v[190:193], v[126:129]
	v_mfma_f32_16x16x32_bf16 v[126:129], v[160:163], v[194:197], v[126:129]
	v_mfma_f32_16x16x32_bf16 v[122:125], v[168:171], v[194:197], v[122:125]
	v_mfma_f32_16x16x32_bf16 v[122:125], v[164:167], v[190:193], v[122:125]
	v_mfma_f32_16x16x32_bf16 v[118:121], v[174:177], v[190:193], v[118:121]
	v_mfma_f32_16x16x32_bf16 v[118:121], v[178:181], v[194:197], v[118:121]
	v_mfma_f32_16x16x32_bf16 v[114:117], v[186:189], v[194:197], v[114:117]
	v_mfma_f32_16x16x32_bf16 v[114:117], v[182:185], v[190:193], v[114:117]
	v_mfma_f32_16x16x32_bf16 v[98:101], v[182:185], v[198:201], v[98:101]
	v_mfma_f32_16x16x32_bf16 v[98:101], v[186:189], v[202:205], v[98:101]
	v_mfma_f32_16x16x32_bf16 v[102:105], v[178:181], v[202:205], v[102:105]
	v_mfma_f32_16x16x32_bf16 v[102:105], v[174:177], v[198:201], v[102:105]
	v_mfma_f32_16x16x32_bf16 v[106:109], v[164:167], v[198:201], v[106:109]
	v_mfma_f32_16x16x32_bf16 v[106:109], v[168:171], v[202:205], v[106:109]
	v_mfma_f32_16x16x32_bf16 v[110:113], v[160:163], v[202:205], v[110:113]
	v_mfma_f32_16x16x32_bf16 v[110:113], v[156:159], v[198:201], v[110:113]
	v_mfma_f32_16x16x32_bf16 v[94:97], v[156:159], v[206:209], v[94:97]
	v_mfma_f32_16x16x32_bf16 v[94:97], v[160:163], v[210:213], v[94:97]
	v_mfma_f32_16x16x32_bf16 v[90:93], v[168:171], v[210:213], v[90:93]
	v_mfma_f32_16x16x32_bf16 v[90:93], v[164:167], v[206:209], v[90:93]
	v_mfma_f32_16x16x32_bf16 v[86:89], v[174:177], v[206:209], v[86:89]
	v_mfma_f32_16x16x32_bf16 v[86:89], v[178:181], v[210:213], v[86:89]
	v_mfma_f32_16x16x32_bf16 v[82:85], v[186:189], v[210:213], v[82:85]
	v_mfma_f32_16x16x32_bf16 v[82:85], v[182:185], v[206:209], v[82:85]
	v_mfma_f32_16x16x32_bf16 v[66:69], v[182:185], v[214:217], v[66:69]
	v_mfma_f32_16x16x32_bf16 v[66:69], v[186:189], v[218:221], v[66:69]
	v_mfma_f32_16x16x32_bf16 v[70:73], v[178:181], v[218:221], v[70:73]
	v_mfma_f32_16x16x32_bf16 v[70:73], v[174:177], v[214:217], v[70:73]
	v_mfma_f32_16x16x32_bf16 v[74:77], v[164:167], v[214:217], v[74:77]
	v_mfma_f32_16x16x32_bf16 v[74:77], v[168:171], v[218:221], v[74:77]
	v_mfma_f32_16x16x32_bf16 v[78:81], v[160:163], v[218:221], v[78:81]
	v_mfma_f32_16x16x32_bf16 v[78:81], v[156:159], v[214:217], v[78:81]
	v_mfma_f32_16x16x32_bf16 v[62:65], v[156:159], v[222:225], v[62:65]
	v_mfma_f32_16x16x32_bf16 v[62:65], v[160:163], v[226:229], v[62:65]
	v_mfma_f32_16x16x32_bf16 v[58:61], v[168:171], v[226:229], v[58:61]
	v_mfma_f32_16x16x32_bf16 v[58:61], v[164:167], v[222:225], v[58:61]
	v_mfma_f32_16x16x32_bf16 v[54:57], v[174:177], v[222:225], v[54:57]
	v_mfma_f32_16x16x32_bf16 v[54:57], v[178:181], v[226:229], v[54:57]
	v_mfma_f32_16x16x32_bf16 v[50:53], v[186:189], v[226:229], v[50:53]
	v_mfma_f32_16x16x32_bf16 v[50:53], v[182:185], v[222:225], v[50:53]
	v_mfma_f32_16x16x32_bf16 v[34:37], v[182:185], v[230:233], v[34:37]
	v_mfma_f32_16x16x32_bf16 v[34:37], v[186:189], v[234:237], v[34:37]
	v_mfma_f32_16x16x32_bf16 v[38:41], v[178:181], v[234:237], v[38:41]
	v_mfma_f32_16x16x32_bf16 v[38:41], v[174:177], v[230:233], v[38:41]
	v_mfma_f32_16x16x32_bf16 v[42:45], v[164:167], v[230:233], v[42:45]
	v_mfma_f32_16x16x32_bf16 v[42:45], v[168:171], v[234:237], v[42:45]
	v_mfma_f32_16x16x32_bf16 v[46:49], v[160:163], v[234:237], v[46:49]
	v_mfma_f32_16x16x32_bf16 v[46:49], v[156:159], v[230:233], v[46:49]
	v_mfma_f32_16x16x32_bf16 v[30:33], v[156:159], v[238:241], v[30:33]
	v_mfma_f32_16x16x32_bf16 v[30:33], v[160:163], v[242:245], v[30:33]
	v_mfma_f32_16x16x32_bf16 v[26:29], v[168:171], v[242:245], v[26:29]
	v_mfma_f32_16x16x32_bf16 v[26:29], v[164:167], v[238:241], v[26:29]
	v_mfma_f32_16x16x32_bf16 v[22:25], v[174:177], v[238:241], v[22:25]
	v_mfma_f32_16x16x32_bf16 v[22:25], v[178:181], v[242:245], v[22:25]
	v_mfma_f32_16x16x32_bf16 v[18:21], v[186:189], v[242:245], v[18:21]
	v_mfma_f32_16x16x32_bf16 v[18:21], v[182:185], v[238:241], v[18:21]
	v_mfma_f32_16x16x32_bf16 v[2:5], v[182:185], v[246:249], v[2:5]
	v_mfma_f32_16x16x32_bf16 v[2:5], v[186:189], v[250:253], v[2:5]
	v_mfma_f32_16x16x32_bf16 v[6:9], v[178:181], v[250:253], v[6:9]
	v_mfma_f32_16x16x32_bf16 v[6:9], v[174:177], v[246:249], v[6:9]
	v_mfma_f32_16x16x32_bf16 v[10:13], v[164:167], v[246:249], v[10:13]
	v_mfma_f32_16x16x32_bf16 v[10:13], v[168:171], v[250:253], v[10:13]
	v_mfma_f32_16x16x32_bf16 v[14:17], v[160:163], v[250:253], v[14:17]
	v_mfma_f32_16x16x32_bf16 v[14:17], v[156:159], v[246:249], v[14:17]
	s_setprio 0
	s_waitcnt vmcnt(0)
	s_barrier
	s_add_i32 s49, s49, 1

;     __host__ __device__ bool next(int i, Unit& u) const { const int L = i * G + c; if (L >= n) return false; u.pm = L; u.pn = L >> 2; return true; }
; #define PG8_STAGE(bufoff, gbase, voff) do { _Pragma("unroll") for (int _i = 0; _i < 2; ++_i) \
;         __builtin_amdgcn_global_load_lds((const unsigned*)((const char*)(gbase) + (voff)[_i]), (PG8_LAS unsigned*)(lds + (bufoff) + ldsw + _i * 8192), 16, 0, 0); } while (0)
; #define PG8_LDA(dst, b, h) do { _Pragma("unroll") for (int m = 0; m < 4; ++m) _Pragma("unroll") for (int k = 0; k < 2; ++k) dst[m][k] = *(const PG8_LAS bf16x8*)(lds + PG8_SA(b, h) + aoff + m * 2048 + k * 1024); } while (0)
; #define PG8_LDB(dst, b, h) do { _Pragma("unroll") for (int n = 0; n < 2; ++n) _Pragma("unroll") for (int k = 0; k < 2; ++k) dst[n][k] = *(const PG8_LAS bf16x8*)(lds + PG8_SB(b, h) + boff + n * 2048 + k * 1024); } while (0)
; #define PG8_WAIT_V(n) asm volatile("s_waitcnt vmcnt(" #n ")" ::: "memory")
; template <class Epi, class Sched, bool ALIGN_EPI>
; __device__ __forceinline__ void gemm_phase(PG8_LAS unsigned char* lds, const Gemm g, const Sched& S, const Epi& E) {
;     ...
;         const bool has_next = S.next(ui + 1, nxt);
;         const size_t tail_ = has_next ? 0 : tailoff; const char* nA = (has_next ? (const char*)g.A + (size_t)nxt.pm * tstepA : cA) + (has_next ? 0 : tailoffA); const char* nB = (has_next ? (const char*)g.Bt + (size_t)nxt.pn * tstepB : cB) + tail_;
;         for (int t = 0; t < nt; t += 2) {
;             if constexpr (Epi::MIDK) { if (t == (nt >> 1)) E.midk(acc, cur, wr, fr); }
;             const bool last = (t == nt - 2);
;             const char* a1 = cA + (size_t)(t + 1) * kstepA;
;             const char* a2 = last ? nA : cA + (size_t)(t + 2) * kstepA; const char* b2 = last ? nB : cB + (size_t)(t + 2) * kstep;
;             const char* a3 = a2 + kstepA; const char* b3 = b2 + kstep;
;             PG8_LDB(B0, 0, 0); PG8_LDB(B1, 0, 1); PG8_SCHED; PG8_LDA(At, 0, 0); PG8_STAGE(PG8_SA(1, 1), a1 + hstepA, voffA);
;             PG8_WAIT_V(8); PG8_WAIT_L(0); PG8_BAR; PG8_MMA(0, 0, At, B0); PG8_MMA(0, 1, At, B1); PG8_BAR; PG8_SCHED;
;             PG8_LDA(At, 0, 1); PG8_STAGE(PG8_SB(0, 0), b2, voffB); PG8_STAGE(PG8_SB(0, 1), b2 + hstepB, voffB); PG8_STAGE(PG8_SA(0, 0), a2, voffA);
;             PG8_WAIT_V(8); PG8_WAIT_L(0); PG8_BAR; PG8_MMA(1, 0, At, B0); PG8_MMA(1, 1, At, B1); PG8_BAR; PG8_SCHED;
.LBB0_947:
	s_add_u32 s6, s6, s30
	s_addc_u32 s7, s7, s31
	s_add_u32 s24, s34, s24
	s_addc_u32 s25, s35, s25
	s_add_u32 s57, s28, 0x100
	s_addc_u32 s58, s29, 0
	s_mov_b32 s59, -2
	s_and_b32 s60, s37, 0xfff
	s_mov_b32 s57, 0
	s_cmp_lt_u32 s37, 0x1000
	s_cbranch_scc0 .Lp9k_B_init
	s_add_u32 s28, s28, 0x80
	s_addc_u32 s29, s29, 0
	s_mov_b64 s[58:59], s[24:25]
	ds_read_b128 v[194:197], v157 offset:0
	ds_read_b128 v[198:201], v157 offset:1024
	ds_read_b128 v[202:205], v157 offset:2048
	s_add_i32 m0, s60, 0x18000
	s_nop 0
	global_load_lds_dwordx4 v132, s[28:29]
	ds_read_b128 v[206:209], v157 offset:3072
	ds_read_b128 v[210:213], v157 offset:4096
	ds_read_b128 v[214:217], v157 offset:5120
	s_add_i32 m0, s60, 0x1a000
	s_nop 0
	global_load_lds_dwordx4 v136, s[28:29]
	ds_read_b128 v[218:221], v157 offset:6144
	ds_read_b128 v[222:225], v157 offset:7168
	ds_read_b128 v[158:161], v155 offset:0
	s_add_u32 s30, s28, 0x58000
	s_addc_u32 s31, s29, 0
	s_add_i32 m0, s60, 0x19000
	s_nop 0
	global_load_lds_dwordx4 v132, s[30:31]
	ds_read_b128 v[162:165], v155 offset:1024
	ds_read_b128 v[166:169], v155 offset:2048
	ds_read_b128 v[174:177], v155 offset:3072
	s_add_i32 m0, s60, 0x1b000
	s_nop 0
	global_load_lds_dwordx4 v136, s[30:31]
	ds_read_b128 v[178:181], v155 offset:16384
	ds_read_b128 v[182:185], v155 offset:17408
	ds_read_b128 v[186:189], v155 offset:18432
	s_add_u32 s30, s28, 0x160000
	s_addc_u32 s31, s29, 0
	s_add_i32 m0, s60, 0x1c000
	s_nop 0
	global_load_lds_dwordx4 v132, s[30:31]
	ds_read_b128 v[190:193], v155 offset:19456
	ds_read_b128 v[226:229], v157 offset:16384
	ds_read_b128 v[230:233], v157 offset:17408
	s_add_i32 m0, s60, 0x1e000
	s_nop 0
	global_load_lds_dwordx4 v136, s[30:31]
	ds_read_b128 v[234:237], v157 offset:18432
	ds_read_b128 v[238:241], v157 offset:19456
	ds_read_b128 v[242:245], v157 offset:20480
	s_add_u32 s30, s28, 0x1b8000
	s_addc_u32 s31, s29, 0
	s_add_i32 m0, s60, 0x1d000
	s_nop 0
	global_load_lds_dwordx4 v132, s[30:31]
	ds_read_b128 v[246:249], v157 offset:21504
	ds_read_b128 v[250:253], v157 offset:22528
	ds_read_b128 v[142:145], v157 offset:23552
	s_add_i32 m0, s60, 0x1f000
	s_nop 0
	global_load_lds_dwordx4 v136, s[30:31]
	s_add_u32 s28, s28, 0x80
	s_addc_u32 s29, s29, 0
	s_waitcnt vmcnt(8) lgkmcnt(0)
	s_barrier
	s_setprio 1
	v_mfma_f32_16x16x32_bf16 v[126:129], v[158:161], v[194:197], 0
	v_mfma_f32_16x16x32_bf16 v[126:129], v[162:165], v[198:201], v[126:129]
	v_mfma_f32_16x16x32_bf16 v[122:125], v[174:177], v[198:201], 0
	v_mfma_f32_16x16x32_bf16 v[122:125], v[166:169], v[194:197], v[122:125]
	v_mfma_f32_16x16x32_bf16 v[114:117], v[178:181], v[194:197], 0
	v_mfma_f32_16x16x32_bf16 v[114:117], v[182:185], v[198:201], v[114:117]
	v_mfma_f32_16x16x32_bf16 v[106:109], v[190:193], v[198:201], 0
	v_mfma_f32_16x16x32_bf16 v[106:109], v[186:189], v[194:197], v[106:109]
	v_mfma_f32_16x16x32_bf16 v[90:93], v[186:189], v[202:205], 0
	v_mfma_f32_16x16x32_bf16 v[90:93], v[190:193], v[206:209], v[90:93]
	v_mfma_f32_16x16x32_bf16 v[98:101], v[182:185], v[206:209], 0
	v_mfma_f32_16x16x32_bf16 v[98:101], v[178:181], v[202:205], v[98:101]
	v_mfma_f32_16x16x32_bf16 v[110:113], v[166:169], v[202:205], 0
	v_mfma_f32_16x16x32_bf16 v[110:113], v[174:177], v[206:209], v[110:113]
	v_mfma_f32_16x16x32_bf16 v[118:121], v[162:165], v[206:209], 0
	v_mfma_f32_16x16x32_bf16 v[118:121], v[158:161], v[202:205], v[118:121]
	v_mfma_f32_16x16x32_bf16 v[102:105], v[158:161], v[210:213], 0
	v_mfma_f32_16x16x32_bf16 v[102:105], v[162:165], v[214:217], v[102:105]
	v_mfma_f32_16x16x32_bf16 v[94:97], v[174:177], v[214:217], 0
	v_mfma_f32_16x16x32_bf16 v[94:97], v[166:169], v[210:213], v[94:97]
	v_mfma_f32_16x16x32_bf16 v[82:85], v[178:181], v[210:213], 0
	v_mfma_f32_16x16x32_bf16 v[82:85], v[182:185], v[214:217], v[82:85]
	v_mfma_f32_16x16x32_bf16 v[74:77], v[190:193], v[214:217], 0
	v_mfma_f32_16x16x32_bf16 v[74:77], v[186:189], v[210:213], v[74:77]
	v_mfma_f32_16x16x32_bf16 v[66:69], v[186:189], v[218:221], 0
	v_mfma_f32_16x16x32_bf16 v[66:69], v[190:193], v[222:225], v[66:69]
	v_mfma_f32_16x16x32_bf16 v[70:73], v[182:185], v[222:225], 0
	v_mfma_f32_16x16x32_bf16 v[70:73], v[178:181], v[218:221], v[70:73]
	v_mfma_f32_16x16x32_bf16 v[78:81], v[166:169], v[218:221], 0
	v_mfma_f32_16x16x32_bf16 v[78:81], v[174:177], v[222:225], v[78:81]
	v_mfma_f32_16x16x32_bf16 v[86:89], v[162:165], v[222:225], 0
	v_mfma_f32_16x16x32_bf16 v[86:89], v[158:161], v[218:221], v[86:89]
	v_mfma_f32_16x16x32_bf16 v[62:65], v[158:161], v[226:229], 0
	v_mfma_f32_16x16x32_bf16 v[62:65], v[162:165], v[230:233], v[62:65]
	v_mfma_f32_16x16x32_bf16 v[58:61], v[174:177], v[230:233], 0
	v_mfma_f32_16x16x32_bf16 v[58:61], v[166:169], v[226:229], v[58:61]
	v_mfma_f32_16x16x32_bf16 v[50:53], v[178:181], v[226:229], 0
	v_mfma_f32_16x16x32_bf16 v[50:53], v[182:185], v[230:233], v[50:53]
	v_mfma_f32_16x16x32_bf16 v[42:45], v[190:193], v[230:233], 0
	v_mfma_f32_16x16x32_bf16 v[42:45], v[186:189], v[226:229], v[42:45]
	v_mfma_f32_16x16x32_bf16 v[26:29], v[186:189], v[234:237], 0
	v_mfma_f32_16x16x32_bf16 v[26:29], v[190:193], v[238:241], v[26:29]
	v_mfma_f32_16x16x32_bf16 v[34:37], v[182:185], v[238:241], 0
	v_mfma_f32_16x16x32_bf16 v[34:37], v[178:181], v[234:237], v[34:37]
	v_mfma_f32_16x16x32_bf16 v[46:49], v[166:169], v[234:237], 0
	v_mfma_f32_16x16x32_bf16 v[46:49], v[174:177], v[238:241], v[46:49]
	v_mfma_f32_16x16x32_bf16 v[54:57], v[162:165], v[238:241], 0
	v_mfma_f32_16x16x32_bf16 v[54:57], v[158:161], v[234:237], v[54:57]
	v_mfma_f32_16x16x32_bf16 v[38:41], v[158:161], v[242:245], 0
	v_mfma_f32_16x16x32_bf16 v[38:41], v[162:165], v[246:249], v[38:41]
	v_mfma_f32_16x16x32_bf16 v[30:33], v[174:177], v[246:249], 0
	v_mfma_f32_16x16x32_bf16 v[30:33], v[166:169], v[242:245], v[30:33]
	v_mfma_f32_16x16x32_bf16 v[18:21], v[178:181], v[242:245], 0
	v_mfma_f32_16x16x32_bf16 v[18:21], v[182:185], v[246:249], v[18:21]
	v_mfma_f32_16x16x32_bf16 v[10:13], v[190:193], v[246:249], 0
	v_mfma_f32_16x16x32_bf16 v[10:13], v[186:189], v[242:245], v[10:13]
	v_mfma_f32_16x16x32_bf16 v[2:5], v[186:189], v[250:253], 0
	v_mfma_f32_16x16x32_bf16 v[2:5], v[190:193], v[142:145], v[2:5]
	v_mfma_f32_16x16x32_bf16 v[6:9], v[182:185], v[142:145], 0
	v_mfma_f32_16x16x32_bf16 v[6:9], v[178:181], v[250:253], v[6:9]
	v_mfma_f32_16x16x32_bf16 v[14:17], v[166:169], v[250:253], 0
	v_mfma_f32_16x16x32_bf16 v[14:17], v[174:177], v[142:145], v[14:17]
	v_mfma_f32_16x16x32_bf16 v[22:25], v[162:165], v[142:145], 0
	v_mfma_f32_16x16x32_bf16 v[22:25], v[158:161], v[250:253], v[22:25]
	s_setprio 0
	s_waitcnt vmcnt(0)
	s_barrier
; #define PG8_STAGE(bufoff, gbase, voff) do { _Pragma("unroll") for (int _i = 0; _i < 2; ++_i) \
;         __builtin_amdgcn_global_load_lds((const unsigned*)((const char*)(gbase) + (voff)[_i]), (PG8_LAS unsigned*)(lds + (bufoff) + ldsw + _i * 8192), 16, 0, 0); } while (0)
; #define PG8_LDA(dst, b, h) do { _Pragma("unroll") for (int m = 0; m < 4; ++m) _Pragma("unroll") for (int k = 0; k < 2; ++k) dst[m][k] = *(const PG8_LAS bf16x8*)(lds + PG8_SA(b, h) + aoff + m * 2048 + k * 1024); } while (0)
; #define PG8_LDB(dst, b, h) do { _Pragma("unroll") for (int n = 0; n < 2; ++n) _Pragma("unroll") for (int k = 0; k < 2; ++k) dst[n][k] = *(const PG8_LAS bf16x8*)(lds + PG8_SB(b, h) + boff + n * 2048 + k * 1024); } while (0)
; #define PG8_MMA(ai, bj, At, Bt) do { __builtin_amdgcn_s_setprio(1); _Pragma("unroll") for (int m = 0; m < 4; ++m) _Pragma("unroll") for (int n = 0; n < 2; ++n) _Pragma("unroll") for (int k = 0; k < 2; ++k) \
;         acc[ai][bj][m][n] = __builtin_amdgcn_mfma_f32_16x16x32_bf16(Bt[n][k], At[m][k], acc[ai][bj][m][n], 0, 0, 0); __builtin_amdgcn_s_setprio(0); } while (0)
; #define PG8_WAIT_V(n) asm volatile("s_waitcnt vmcnt(" #n ")" ::: "memory")
; #define PG8_WAIT_L(n) asm volatile("s_waitcnt lgkmcnt(" #n ")" ::: "memory")
; #define PG8_BAR __builtin_amdgcn_s_barrier()
; #define PG8_SCHED __builtin_amdgcn_sched_barrier(0)
; template <class Epi, class Sched, bool ALIGN_EPI>
; __device__ __forceinline__ void gemm_phase(PG8_LAS unsigned char* lds, const Gemm g, const Sched& S, const Epi& E) {
;     ...
;             PG8_LDB(B0, 1, 0); PG8_LDB(B1, 1, 1); PG8_SCHED; PG8_LDA(At, 1, 0); PG8_STAGE(PG8_SA(0, 1), a2 + hstepA, voffA);
;             PG8_WAIT_V(8); PG8_WAIT_L(0); PG8_BAR; PG8_MMA(0, 0, At, B0); PG8_MMA(0, 1, At, B1); PG8_BAR; PG8_SCHED;
;             PG8_LDA(At, 1, 1); PG8_STAGE(PG8_SB(1, 0), b3, voffB); PG8_STAGE(PG8_SB(1, 1), b3 + hstepB, voffB); PG8_STAGE(PG8_SA(1, 0), a3, voffA);
;             PG8_WAIT_V(8); PG8_WAIT_L(0); PG8_BAR; PG8_MMA(1, 0, At, B0); PG8_MMA(1, 1, At, B1); PG8_BAR; PG8_SCHED;
	ds_read_b128 v[194:197], v157 offset:32768
	ds_read_b128 v[198:201], v157 offset:33792
	ds_read_b128 v[202:205], v157 offset:34816
	s_cmp_eq_u32 s57, 43
	s_cselect_b32 s28, s58, s28
	s_cselect_b32 s29, s59, s29
	s_add_i32 m0, s60, 0x10000
	s_nop 0
	global_load_lds_dwordx4 v132, s[28:29]
	ds_read_b128 v[206:209], v157 offset:35840
	ds_read_b128 v[210:213], v157 offset:36864
	ds_read_b128 v[214:217], v157 offset:37888
	s_add_i32 m0, s60, 0x12000
	s_nop 0
	global_load_lds_dwordx4 v136, s[28:29]
	ds_read_b128 v[218:221], v157 offset:38912
	ds_read_b128 v[222:225], v157 offset:39936
	ds_read_b128 v[158:161], v155 offset:32768
	s_add_u32 s30, s28, 0x58000
	s_addc_u32 s31, s29, 0
	s_add_i32 m0, s60, 0x11000
	s_nop 0
	global_load_lds_dwordx4 v132, s[30:31]
	ds_read_b128 v[162:165], v155 offset:33792
	ds_read_b128 v[166:169], v155 offset:34816
	ds_read_b128 v[174:177], v155 offset:35840
	s_add_i32 m0, s60, 0x13000
	s_nop 0
	global_load_lds_dwordx4 v136, s[30:31]
	ds_read_b128 v[178:181], v155 offset:49152
	ds_read_b128 v[182:185], v155 offset:50176
	ds_read_b128 v[186:189], v155 offset:51200
	s_add_u32 s30, s28, 0x160000
	s_addc_u32 s31, s29, 0
	s_add_i32 m0, s60, 0x14000
	s_nop 0
	global_load_lds_dwordx4 v132, s[30:31]
	ds_read_b128 v[190:193], v155 offset:52224
	ds_read_b128 v[226:229], v157 offset:49152
	ds_read_b128 v[230:233], v157 offset:50176
	s_add_i32 m0, s60, 0x16000
	s_nop 0
	global_load_lds_dwordx4 v136, s[30:31]
	ds_read_b128 v[234:237], v157 offset:51200
	ds_read_b128 v[238:241], v157 offset:52224
	ds_read_b128 v[242:245], v157 offset:53248
	s_add_u32 s30, s28, 0x1b8000
	s_addc_u32 s31, s29, 0
	s_add_i32 m0, s60, 0x15000
	s_nop 0
	global_load_lds_dwordx4 v132, s[30:31]
	ds_read_b128 v[246:249], v157 offset:54272
	ds_read_b128 v[250:253], v157 offset:55296
	ds_read_b128 v[142:145], v157 offset:56320
	s_add_i32 m0, s60, 0x17000
	s_nop 0
	global_load_lds_dwordx4 v136, s[30:31]
	s_add_u32 s28, s28, 0x80
	s_addc_u32 s29, s29, 0
	s_waitcnt vmcnt(8) lgkmcnt(0)
	s_barrier
	s_setprio 1
	v_mfma_f32_16x16x32_bf16 v[126:129], v[158:161], v[194:197], v[126:129]
	v_mfma_f32_16x16x32_bf16 v[126:129], v[162:165], v[198:201], v[126:129]
	v_mfma_f32_16x16x32_bf16 v[122:125], v[174:177], v[198:201], v[122:125]
	v_mfma_f32_16x16x32_bf16 v[122:125], v[166:169], v[194:197], v[122:125]
	v_mfma_f32_16x16x32_bf16 v[114:117], v[178:181], v[194:197], v[114:117]
	v_mfma_f32_16x16x32_bf16 v[114:117], v[182:185], v[198:201], v[114:117]
	v_mfma_f32_16x16x32_bf16 v[106:109], v[190:193], v[198:201], v[106:109]
	v_mfma_f32_16x16x32_bf16 v[106:109], v[186:189], v[194:197], v[106:109]
	v_mfma_f32_16x16x32_bf16 v[90:93], v[186:189], v[202:205], v[90:93]
	v_mfma_f32_16x16x32_bf16 v[90:93], v[190:193], v[206:209], v[90:93]
	v_mfma_f32_16x16x32_bf16 v[98:101], v[182:185], v[206:209], v[98:101]
	v_mfma_f32_16x16x32_bf16 v[98:101], v[178:181], v[202:205], v[98:101]
	v_mfma_f32_16x16x32_bf16 v[110:113], v[166:169], v[202:205], v[110:113]
	v_mfma_f32_16x16x32_bf16 v[110:113], v[174:177], v[206:209], v[110:113]
	v_mfma_f32_16x16x32_bf16 v[118:121], v[162:165], v[206:209], v[118:121]
	v_mfma_f32_16x16x32_bf16 v[118:121], v[158:161], v[202:205], v[118:121]
	v_mfma_f32_16x16x32_bf16 v[102:105], v[158:161], v[210:213], v[102:105]
	v_mfma_f32_16x16x32_bf16 v[102:105], v[162:165], v[214:217], v[102:105]
	v_mfma_f32_16x16x32_bf16 v[94:97], v[174:177], v[214:217], v[94:97]
	v_mfma_f32_16x16x32_bf16 v[94:97], v[166:169], v[210:213], v[94:97]
	v_mfma_f32_16x16x32_bf16 v[82:85], v[178:181], v[210:213], v[82:85]
	v_mfma_f32_16x16x32_bf16 v[82:85], v[182:185], v[214:217], v[82:85]
	v_mfma_f32_16x16x32_bf16 v[74:77], v[190:193], v[214:217], v[74:77]
	v_mfma_f32_16x16x32_bf16 v[74:77], v[186:189], v[210:213], v[74:77]
	v_mfma_f32_16x16x32_bf16 v[66:69], v[186:189], v[218:221], v[66:69]
	v_mfma_f32_16x16x32_bf16 v[66:69], v[190:193], v[222:225], v[66:69]
	v_mfma_f32_16x16x32_bf16 v[70:73], v[182:185], v[222:225], v[70:73]
	v_mfma_f32_16x16x32_bf16 v[70:73], v[178:181], v[218:221], v[70:73]
	v_mfma_f32_16x16x32_bf16 v[78:81], v[166:169], v[218:221], v[78:81]
	v_mfma_f32_16x16x32_bf16 v[78:81], v[174:177], v[222:225], v[78:81]
	v_mfma_f32_16x16x32_bf16 v[86:89], v[162:165], v[222:225], v[86:89]
	v_mfma_f32_16x16x32_bf16 v[86:89], v[158:161], v[218:221], v[86:89]
	v_mfma_f32_16x16x32_bf16 v[62:65], v[158:161], v[226:229], v[62:65]
	v_mfma_f32_16x16x32_bf16 v[62:65], v[162:165], v[230:233], v[62:65]
	v_mfma_f32_16x16x32_bf16 v[58:61], v[174:177], v[230:233], v[58:61]
	v_mfma_f32_16x16x32_bf16 v[58:61], v[166:169], v[226:229], v[58:61]
	v_mfma_f32_16x16x32_bf16 v[50:53], v[178:181], v[226:229], v[50:53]
	v_mfma_f32_16x16x32_bf16 v[50:53], v[182:185], v[230:233], v[50:53]
	v_mfma_f32_16x16x32_bf16 v[42:45], v[190:193], v[230:233], v[42:45]
	v_mfma_f32_16x16x32_bf16 v[42:45], v[186:189], v[226:229], v[42:45]
	v_mfma_f32_16x16x32_bf16 v[26:29], v[186:189], v[234:237], v[26:29]
	v_mfma_f32_16x16x32_bf16 v[26:29], v[190:193], v[238:241], v[26:29]
	v_mfma_f32_16x16x32_bf16 v[34:37], v[182:185], v[238:241], v[34:37]
	v_mfma_f32_16x16x32_bf16 v[34:37], v[178:181], v[234:237], v[34:37]
	v_mfma_f32_16x16x32_bf16 v[46:49], v[166:169], v[234:237], v[46:49]
	v_mfma_f32_16x16x32_bf16 v[46:49], v[174:177], v[238:241], v[46:49]
	v_mfma_f32_16x16x32_bf16 v[54:57], v[162:165], v[238:241], v[54:57]
	v_mfma_f32_16x16x32_bf16 v[54:57], v[158:161], v[234:237], v[54:57]
	v_mfma_f32_16x16x32_bf16 v[38:41], v[158:161], v[242:245], v[38:41]
	v_mfma_f32_16x16x32_bf16 v[38:41], v[162:165], v[246:249], v[38:41]
	v_mfma_f32_16x16x32_bf16 v[30:33], v[174:177], v[246:249], v[30:33]
	v_mfma_f32_16x16x32_bf16 v[30:33], v[166:169], v[242:245], v[30:33]
	v_mfma_f32_16x16x32_bf16 v[18:21], v[178:181], v[242:245], v[18:21]
	v_mfma_f32_16x16x32_bf16 v[18:21], v[182:185], v[246:249], v[18:21]
	v_mfma_f32_16x16x32_bf16 v[10:13], v[190:193], v[246:249], v[10:13]
	v_mfma_f32_16x16x32_bf16 v[10:13], v[186:189], v[242:245], v[10:13]
	v_mfma_f32_16x16x32_bf16 v[2:5], v[186:189], v[250:253], v[2:5]
	v_mfma_f32_16x16x32_bf16 v[2:5], v[190:193], v[142:145], v[2:5]
	v_mfma_f32_16x16x32_bf16 v[6:9], v[182:185], v[142:145], v[6:9]
	v_mfma_f32_16x16x32_bf16 v[6:9], v[178:181], v[250:253], v[6:9]
	v_mfma_f32_16x16x32_bf16 v[14:17], v[166:169], v[250:253], v[14:17]
	v_mfma_f32_16x16x32_bf16 v[14:17], v[174:177], v[142:145], v[14:17]
	v_mfma_f32_16x16x32_bf16 v[22:25], v[162:165], v[142:145], v[22:25]
	v_mfma_f32_16x16x32_bf16 v[22:25], v[158:161], v[250:253], v[22:25]
	s_setprio 0
	s_waitcnt vmcnt(0)
	s_barrier
	s_add_i32 s57, s57, 1

; #define PG8_STAGE(bufoff, gbase, voff) do { _Pragma("unroll") for (int _i = 0; _i < 2; ++_i) \
;         __builtin_amdgcn_global_load_lds((const unsigned*)((const char*)(gbase) + (voff)[_i]), (PG8_LAS unsigned*)(lds + (bufoff) + ldsw + _i * 8192), 16, 0, 0); } while (0)
; #define PG8_LDA(dst, b, h) do { _Pragma("unroll") for (int m = 0; m < 4; ++m) _Pragma("unroll") for (int k = 0; k < 2; ++k) dst[m][k] = *(const PG8_LAS bf16x8*)(lds + PG8_SA(b, h) + aoff + m * 2048 + k * 1024); } while (0)
; #define PG8_LDB(dst, b, h) do { _Pragma("unroll") for (int n = 0; n < 2; ++n) _Pragma("unroll") for (int k = 0; k < 2; ++k) dst[n][k] = *(const PG8_LAS bf16x8*)(lds + PG8_SB(b, h) + boff + n * 2048 + k * 1024); } while (0)
; #define PG8_MMA(ai, bj, At, Bt) do { __builtin_amdgcn_s_setprio(1); _Pragma("unroll") for (int m = 0; m < 4; ++m) _Pragma("unroll") for (int n = 0; n < 2; ++n) _Pragma("unroll") for (int k = 0; k < 2; ++k) \
;         acc[ai][bj][m][n] = __builtin_amdgcn_mfma_f32_16x16x32_bf16(Bt[n][k], At[m][k], acc[ai][bj][m][n], 0, 0, 0); __builtin_amdgcn_s_setprio(0); } while (0)
; #define PG8_WAIT_V(n) asm volatile("s_waitcnt vmcnt(" #n ")" ::: "memory")
; #define PG8_WAIT_L(n) asm volatile("s_waitcnt lgkmcnt(" #n ")" ::: "memory")
; #define PG8_BAR __builtin_amdgcn_s_barrier()
; #define PG8_SCHED __builtin_amdgcn_sched_barrier(0)
; template <class Epi, class Sched, bool ALIGN_EPI>
; __device__ __forceinline__ void gemm_phase(PG8_LAS unsigned char* lds, const Gemm g, const Sched& S, const Epi& E) {
;     ...
;             const char* a2 = last ? nA : cA + (size_t)(t + 2) * kstepA; const char* b2 = last ? nB : cB + (size_t)(t + 2) * kstep;
;             const char* a3 = a2 + kstepA; const char* b3 = b2 + kstep;
;             PG8_LDB(B0, 0, 0); PG8_LDB(B1, 0, 1); PG8_SCHED; PG8_LDA(At, 0, 0); PG8_STAGE(PG8_SA(1, 1), a1 + hstepA, voffA);
;             PG8_WAIT_V(8); PG8_WAIT_L(0); PG8_BAR; PG8_MMA(0, 0, At, B0); PG8_MMA(0, 1, At, B1); PG8_BAR; PG8_SCHED;
;             PG8_LDA(At, 0, 1); PG8_STAGE(PG8_SB(0, 0), b2, voffB); PG8_STAGE(PG8_SB(0, 1), b2 + hstepB, voffB); PG8_STAGE(PG8_SA(0, 0), a2, voffA);
;             PG8_WAIT_V(8); PG8_WAIT_L(0); PG8_BAR; PG8_MMA(1, 0, At, B0); PG8_MMA(1, 1, At, B1); PG8_BAR; PG8_SCHED;
.Lp9k_B_init:
	s_sub_u32 s28, s26, 0x57f80
	s_subb_u32 s29, s27, 0
	s_sub_u32 s58, s6, 0x58000
	s_subb_u32 s59, s7, 0
	ds_read_b128 v[194:197], v157 offset:0
	ds_read_b128 v[198:201], v157 offset:1024
	ds_read_b128 v[202:205], v157 offset:2048
	s_add_i32 m0, s60, 0xa000
	s_nop 0
	global_load_lds_dwordx4 v134, s[28:29]
	ds_read_b128 v[206:209], v157 offset:3072
	ds_read_b128 v[210:213], v157 offset:4096
	ds_read_b128 v[214:217], v157 offset:5120
	s_add_u32 s30, s28, 0x58000
	s_addc_u32 s31, s29, 0
	s_add_i32 m0, s60, 0xb000
	s_nop 0
	global_load_lds_dwordx4 v134, s[30:31]
	ds_read_b128 v[218:221], v157 offset:6144
	ds_read_b128 v[222:225], v157 offset:7168
	ds_read_b128 v[158:161], v155 offset:0
	s_add_u32 s30, s28, 0x160000
	s_addc_u32 s31, s29, 0
	s_add_i32 m0, s60, 0xe000
	s_nop 0
	global_load_lds_dwordx4 v134, s[30:31]
	ds_read_b128 v[162:165], v155 offset:1024
	ds_read_b128 v[166:169], v155 offset:2048
	ds_read_b128 v[174:177], v155 offset:3072
	s_add_u32 s30, s28, 0x1b8000
	s_addc_u32 s31, s29, 0
	s_add_i32 m0, s60, 0xf000
	s_nop 0
	global_load_lds_dwordx4 v134, s[30:31]
	ds_read_b128 v[178:181], v155 offset:16384
	ds_read_b128 v[182:185], v155 offset:17408
	ds_read_b128 v[186:189], v155 offset:18432
	s_add_u32 s34, s28, 0x80
	s_addc_u32 s35, s29, 0
	s_cmp_eq_u32 s57, 43
	s_cselect_b32 s34, s58, s34
	s_cselect_b32 s35, s59, s35
	s_add_i32 m0, s60, 0x0
	s_nop 0
	global_load_lds_dwordx4 v130, s[34:35]
	ds_read_b128 v[190:193], v155 offset:19456
	ds_read_b128 v[226:229], v157 offset:16384
	ds_read_b128 v[230:233], v157 offset:17408
	s_add_u32 s30, s34, 0x58000
	s_addc_u32 s31, s35, 0
	s_add_i32 m0, s60, 0x1000
	s_nop 0
	global_load_lds_dwordx4 v130, s[30:31]
	ds_read_b128 v[234:237], v157 offset:18432
	ds_read_b128 v[238:241], v157 offset:19456
	ds_read_b128 v[242:245], v157 offset:20480
	s_add_u32 s30, s34, 0x160000
	s_addc_u32 s31, s35, 0
	s_add_i32 m0, s60, 0x4000
	s_nop 0
	global_load_lds_dwordx4 v130, s[30:31]
	ds_read_b128 v[246:249], v157 offset:21504
	ds_read_b128 v[250:253], v157 offset:22528
	ds_read_b128 v[142:145], v157 offset:23552
	s_add_u32 s30, s34, 0x1b8000
	s_addc_u32 s31, s35, 0
	s_add_i32 m0, s60, 0x5000
	s_nop 0
	global_load_lds_dwordx4 v130, s[30:31]
	s_add_u32 s28, s28, 0x80
	s_addc_u32 s29, s29, 0
	s_waitcnt vmcnt(8) lgkmcnt(0)
	s_barrier
	s_setprio 1
	v_mfma_f32_16x16x32_bf16 v[126:129], v[158:161], v[194:197], 0
	v_mfma_f32_16x16x32_bf16 v[126:129], v[162:165], v[198:201], v[126:129]
	v_mfma_f32_16x16x32_bf16 v[122:125], v[174:177], v[198:201], 0
	v_mfma_f32_16x16x32_bf16 v[122:125], v[166:169], v[194:197], v[122:125]
	v_mfma_f32_16x16x32_bf16 v[114:117], v[178:181], v[194:197], 0
	v_mfma_f32_16x16x32_bf16 v[114:117], v[182:185], v[198:201], v[114:117]
	v_mfma_f32_16x16x32_bf16 v[106:109], v[190:193], v[198:201], 0
	v_mfma_f32_16x16x32_bf16 v[106:109], v[186:189], v[194:197], v[106:109]
	v_mfma_f32_16x16x32_bf16 v[90:93], v[186:189], v[202:205], 0
	v_mfma_f32_16x16x32_bf16 v[90:93], v[190:193], v[206:209], v[90:93]
	v_mfma_f32_16x16x32_bf16 v[98:101], v[182:185], v[206:209], 0
	v_mfma_f32_16x16x32_bf16 v[98:101], v[178:181], v[202:205], v[98:101]
	v_mfma_f32_16x16x32_bf16 v[110:113], v[166:169], v[202:205], 0
	v_mfma_f32_16x16x32_bf16 v[110:113], v[174:177], v[206:209], v[110:113]
	v_mfma_f32_16x16x32_bf16 v[118:121], v[162:165], v[206:209], 0
	v_mfma_f32_16x16x32_bf16 v[118:121], v[158:161], v[202:205], v[118:121]
	v_mfma_f32_16x16x32_bf16 v[102:105], v[158:161], v[210:213], 0
	v_mfma_f32_16x16x32_bf16 v[102:105], v[162:165], v[214:217], v[102:105]
	v_mfma_f32_16x16x32_bf16 v[94:97], v[174:177], v[214:217], 0
	v_mfma_f32_16x16x32_bf16 v[94:97], v[166:169], v[210:213], v[94:97]
	v_mfma_f32_16x16x32_bf16 v[82:85], v[178:181], v[210:213], 0
	v_mfma_f32_16x16x32_bf16 v[82:85], v[182:185], v[214:217], v[82:85]
	v_mfma_f32_16x16x32_bf16 v[74:77], v[190:193], v[214:217], 0
	v_mfma_f32_16x16x32_bf16 v[74:77], v[186:189], v[210:213], v[74:77]
	v_mfma_f32_16x16x32_bf16 v[66:69], v[186:189], v[218:221], 0
	v_mfma_f32_16x16x32_bf16 v[66:69], v[190:193], v[222:225], v[66:69]
	v_mfma_f32_16x16x32_bf16 v[70:73], v[182:185], v[222:225], 0
	v_mfma_f32_16x16x32_bf16 v[70:73], v[178:181], v[218:221], v[70:73]
	v_mfma_f32_16x16x32_bf16 v[78:81], v[166:169], v[218:221], 0
	v_mfma_f32_16x16x32_bf16 v[78:81], v[174:177], v[222:225], v[78:81]
	v_mfma_f32_16x16x32_bf16 v[86:89], v[162:165], v[222:225], 0
	v_mfma_f32_16x16x32_bf16 v[86:89], v[158:161], v[218:221], v[86:89]
	v_mfma_f32_16x16x32_bf16 v[62:65], v[158:161], v[226:229], 0
	v_mfma_f32_16x16x32_bf16 v[62:65], v[162:165], v[230:233], v[62:65]
	v_mfma_f32_16x16x32_bf16 v[58:61], v[174:177], v[230:233], 0
	v_mfma_f32_16x16x32_bf16 v[58:61], v[166:169], v[226:229], v[58:61]
	v_mfma_f32_16x16x32_bf16 v[50:53], v[178:181], v[226:229], 0
	v_mfma_f32_16x16x32_bf16 v[50:53], v[182:185], v[230:233], v[50:53]
	v_mfma_f32_16x16x32_bf16 v[42:45], v[190:193], v[230:233], 0
	v_mfma_f32_16x16x32_bf16 v[42:45], v[186:189], v[226:229], v[42:45]
	v_mfma_f32_16x16x32_bf16 v[26:29], v[186:189], v[234:237], 0
	v_mfma_f32_16x16x32_bf16 v[26:29], v[190:193], v[238:241], v[26:29]
	v_mfma_f32_16x16x32_bf16 v[34:37], v[182:185], v[238:241], 0
	v_mfma_f32_16x16x32_bf16 v[34:37], v[178:181], v[234:237], v[34:37]
	v_mfma_f32_16x16x32_bf16 v[46:49], v[166:169], v[234:237], 0
	v_mfma_f32_16x16x32_bf16 v[46:49], v[174:177], v[238:241], v[46:49]
	v_mfma_f32_16x16x32_bf16 v[54:57], v[162:165], v[238:241], 0
	v_mfma_f32_16x16x32_bf16 v[54:57], v[158:161], v[234:237], v[54:57]
	v_mfma_f32_16x16x32_bf16 v[38:41], v[158:161], v[242:245], 0
	v_mfma_f32_16x16x32_bf16 v[38:41], v[162:165], v[246:249], v[38:41]
	v_mfma_f32_16x16x32_bf16 v[30:33], v[174:177], v[246:249], 0
	v_mfma_f32_16x16x32_bf16 v[30:33], v[166:169], v[242:245], v[30:33]
	v_mfma_f32_16x16x32_bf16 v[18:21], v[178:181], v[242:245], 0
	v_mfma_f32_16x16x32_bf16 v[18:21], v[182:185], v[246:249], v[18:21]
	v_mfma_f32_16x16x32_bf16 v[10:13], v[190:193], v[246:249], 0
	v_mfma_f32_16x16x32_bf16 v[10:13], v[186:189], v[242:245], v[10:13]
	v_mfma_f32_16x16x32_bf16 v[2:5], v[186:189], v[250:253], 0
	v_mfma_f32_16x16x32_bf16 v[2:5], v[190:193], v[142:145], v[2:5]
	v_mfma_f32_16x16x32_bf16 v[6:9], v[182:185], v[142:145], 0
	v_mfma_f32_16x16x32_bf16 v[6:9], v[178:181], v[250:253], v[6:9]
	v_mfma_f32_16x16x32_bf16 v[14:17], v[166:169], v[250:253], 0
	v_mfma_f32_16x16x32_bf16 v[14:17], v[174:177], v[142:145], v[14:17]
	v_mfma_f32_16x16x32_bf16 v[22:25], v[162:165], v[142:145], 0
	v_mfma_f32_16x16x32_bf16 v[22:25], v[158:161], v[250:253], v[22:25]
	s_setprio 0
	s_waitcnt vmcnt(0)
	s_barrier
; #define PG8_STAGE(bufoff, gbase, voff) do { _Pragma("unroll") for (int _i = 0; _i < 2; ++_i) \
;         __builtin_amdgcn_global_load_lds((const unsigned*)((const char*)(gbase) + (voff)[_i]), (PG8_LAS unsigned*)(lds + (bufoff) + ldsw + _i * 8192), 16, 0, 0); } while (0)
; #define PG8_LDA(dst, b, h) do { _Pragma("unroll") for (int m = 0; m < 4; ++m) _Pragma("unroll") for (int k = 0; k < 2; ++k) dst[m][k] = *(const PG8_LAS bf16x8*)(lds + PG8_SA(b, h) + aoff + m * 2048 + k * 1024); } while (0)
; #define PG8_LDB(dst, b, h) do { _Pragma("unroll") for (int n = 0; n < 2; ++n) _Pragma("unroll") for (int k = 0; k < 2; ++k) dst[n][k] = *(const PG8_LAS bf16x8*)(lds + PG8_SB(b, h) + boff + n * 2048 + k * 1024); } while (0)
; #define PG8_MMA(ai, bj, At, Bt) do { __builtin_amdgcn_s_setprio(1); _Pragma("unroll") for (int m = 0; m < 4; ++m) _Pragma("unroll") for (int n = 0; n < 2; ++n) _Pragma("unroll") for (int k = 0; k < 2; ++k) \
;         acc[ai][bj][m][n] = __builtin_amdgcn_mfma_f32_16x16x32_bf16(Bt[n][k], At[m][k], acc[ai][bj][m][n], 0, 0, 0); __builtin_amdgcn_s_setprio(0); } while (0)
; #define PG8_WAIT_V(n) asm volatile("s_waitcnt vmcnt(" #n ")" ::: "memory")
; #define PG8_WAIT_L(n) asm volatile("s_waitcnt lgkmcnt(" #n ")" ::: "memory")
; #define PG8_BAR __builtin_amdgcn_s_barrier()
; #define PG8_SCHED __builtin_amdgcn_sched_barrier(0)
; template <class Epi, class Sched, bool ALIGN_EPI>
; __device__ __forceinline__ void gemm_phase(PG8_LAS unsigned char* lds, const Gemm g, const Sched& S, const Epi& E) {
;     ...
;             PG8_LDB(B0, 1, 0); PG8_LDB(B1, 1, 1); PG8_SCHED; PG8_LDA(At, 1, 0); PG8_STAGE(PG8_SA(0, 1), a2 + hstepA, voffA);
;             PG8_WAIT_V(8); PG8_WAIT_L(0); PG8_BAR; PG8_MMA(0, 0, At, B0); PG8_MMA(0, 1, At, B1); PG8_BAR; PG8_SCHED;
;             PG8_LDA(At, 1, 1); PG8_STAGE(PG8_SB(1, 0), b3, voffB); PG8_STAGE(PG8_SB(1, 1), b3 + hstepB, voffB); PG8_STAGE(PG8_SA(1, 0), a3, voffA);
;             PG8_WAIT_V(8); PG8_WAIT_L(0); PG8_BAR; PG8_MMA(1, 0, At, B0); PG8_MMA(1, 1, At, B1); PG8_BAR; PG8_SCHED;
	ds_read_b128 v[194:197], v157 offset:32768
	ds_read_b128 v[198:201], v157 offset:33792
	ds_read_b128 v[202:205], v157 offset:34816
	s_cmp_eq_u32 s57, 43
	s_cselect_b32 s28, s58, s28
	s_cselect_b32 s29, s59, s29
	s_add_i32 m0, s60, 0x2000
	s_nop 0
	global_load_lds_dwordx4 v134, s[28:29]
	ds_read_b128 v[206:209], v157 offset:35840
	ds_read_b128 v[210:213], v157 offset:36864
	ds_read_b128 v[214:217], v157 offset:37888
	s_add_u32 s30, s28, 0x58000
	s_addc_u32 s31, s29, 0
	s_add_i32 m0, s60, 0x3000
	s_nop 0
	global_load_lds_dwordx4 v134, s[30:31]
	ds_read_b128 v[218:221], v157 offset:38912
	ds_read_b128 v[222:225], v157 offset:39936
	ds_read_b128 v[158:161], v155 offset:32768
	s_add_u32 s30, s28, 0x160000
	s_addc_u32 s31, s29, 0
	s_add_i32 m0, s60, 0x6000
	s_nop 0
	global_load_lds_dwordx4 v134, s[30:31]
	ds_read_b128 v[162:165], v155 offset:33792
	ds_read_b128 v[166:169], v155 offset:34816
	ds_read_b128 v[174:177], v155 offset:35840
	s_add_u32 s30, s28, 0x1b8000
	s_addc_u32 s31, s29, 0
	s_add_i32 m0, s60, 0x7000
	s_nop 0
	global_load_lds_dwordx4 v134, s[30:31]
	ds_read_b128 v[178:181], v155 offset:49152
	ds_read_b128 v[182:185], v155 offset:50176
	ds_read_b128 v[186:189], v155 offset:51200
	s_add_u32 s34, s28, 0x80
	s_addc_u32 s35, s29, 0
	s_add_i32 m0, s60, 0x8000
	s_nop 0
	global_load_lds_dwordx4 v130, s[34:35]
	ds_read_b128 v[190:193], v155 offset:52224
	ds_read_b128 v[226:229], v157 offset:49152
	ds_read_b128 v[230:233], v157 offset:50176
	s_add_u32 s30, s34, 0x58000
	s_addc_u32 s31, s35, 0
	s_add_i32 m0, s60, 0x9000
	s_nop 0
	global_load_lds_dwordx4 v130, s[30:31]
	ds_read_b128 v[234:237], v157 offset:51200
	ds_read_b128 v[238:241], v157 offset:52224
	ds_read_b128 v[242:245], v157 offset:53248
	s_add_u32 s30, s34, 0x160000
	s_addc_u32 s31, s35, 0
	s_add_i32 m0, s60, 0xc000
	s_nop 0
	global_load_lds_dwordx4 v130, s[30:31]
	ds_read_b128 v[246:249], v157 offset:54272
	ds_read_b128 v[250:253], v157 offset:55296
	ds_read_b128 v[142:145], v157 offset:56320
	s_add_u32 s30, s34, 0x1b8000
	s_addc_u32 s31, s35, 0
	s_add_i32 m0, s60, 0xd000
	s_nop 0
	global_load_lds_dwordx4 v130, s[30:31]
	s_add_u32 s28, s28, 0x80
	s_addc_u32 s29, s29, 0
	s_waitcnt vmcnt(8) lgkmcnt(0)
	s_barrier
	s_setprio 1
	v_mfma_f32_16x16x32_bf16 v[126:129], v[158:161], v[194:197], v[126:129]
	v_mfma_f32_16x16x32_bf16 v[126:129], v[162:165], v[198:201], v[126:129]
	v_mfma_f32_16x16x32_bf16 v[122:125], v[174:177], v[198:201], v[122:125]
	v_mfma_f32_16x16x32_bf16 v[122:125], v[166:169], v[194:197], v[122:125]
	v_mfma_f32_16x16x32_bf16 v[114:117], v[178:181], v[194:197], v[114:117]
	v_mfma_f32_16x16x32_bf16 v[114:117], v[182:185], v[198:201], v[114:117]
	v_mfma_f32_16x16x32_bf16 v[106:109], v[190:193], v[198:201], v[106:109]
	v_mfma_f32_16x16x32_bf16 v[106:109], v[186:189], v[194:197], v[106:109]
	v_mfma_f32_16x16x32_bf16 v[90:93], v[186:189], v[202:205], v[90:93]
	v_mfma_f32_16x16x32_bf16 v[90:93], v[190:193], v[206:209], v[90:93]
	v_mfma_f32_16x16x32_bf16 v[98:101], v[182:185], v[206:209], v[98:101]
	v_mfma_f32_16x16x32_bf16 v[98:101], v[178:181], v[202:205], v[98:101]
	v_mfma_f32_16x16x32_bf16 v[110:113], v[166:169], v[202:205], v[110:113]
	v_mfma_f32_16x16x32_bf16 v[110:113], v[174:177], v[206:209], v[110:113]
	v_mfma_f32_16x16x32_bf16 v[118:121], v[162:165], v[206:209], v[118:121]
	v_mfma_f32_16x16x32_bf16 v[118:121], v[158:161], v[202:205], v[118:121]
	v_mfma_f32_16x16x32_bf16 v[102:105], v[158:161], v[210:213], v[102:105]
	v_mfma_f32_16x16x32_bf16 v[102:105], v[162:165], v[214:217], v[102:105]
	v_mfma_f32_16x16x32_bf16 v[94:97], v[174:177], v[214:217], v[94:97]
	v_mfma_f32_16x16x32_bf16 v[94:97], v[166:169], v[210:213], v[94:97]
	v_mfma_f32_16x16x32_bf16 v[82:85], v[178:181], v[210:213], v[82:85]
	v_mfma_f32_16x16x32_bf16 v[82:85], v[182:185], v[214:217], v[82:85]
	v_mfma_f32_16x16x32_bf16 v[74:77], v[190:193], v[214:217], v[74:77]
	v_mfma_f32_16x16x32_bf16 v[74:77], v[186:189], v[210:213], v[74:77]
	v_mfma_f32_16x16x32_bf16 v[66:69], v[186:189], v[218:221], v[66:69]
	v_mfma_f32_16x16x32_bf16 v[66:69], v[190:193], v[222:225], v[66:69]
	v_mfma_f32_16x16x32_bf16 v[70:73], v[182:185], v[222:225], v[70:73]
	v_mfma_f32_16x16x32_bf16 v[70:73], v[178:181], v[218:221], v[70:73]
	v_mfma_f32_16x16x32_bf16 v[78:81], v[166:169], v[218:221], v[78:81]
	v_mfma_f32_16x16x32_bf16 v[78:81], v[174:177], v[222:225], v[78:81]
	v_mfma_f32_16x16x32_bf16 v[86:89], v[162:165], v[222:225], v[86:89]
	v_mfma_f32_16x16x32_bf16 v[86:89], v[158:161], v[218:221], v[86:89]
	v_mfma_f32_16x16x32_bf16 v[62:65], v[158:161], v[226:229], v[62:65]
	v_mfma_f32_16x16x32_bf16 v[62:65], v[162:165], v[230:233], v[62:65]
	v_mfma_f32_16x16x32_bf16 v[58:61], v[174:177], v[230:233], v[58:61]
	v_mfma_f32_16x16x32_bf16 v[58:61], v[166:169], v[226:229], v[58:61]
	v_mfma_f32_16x16x32_bf16 v[50:53], v[178:181], v[226:229], v[50:53]
	v_mfma_f32_16x16x32_bf16 v[50:53], v[182:185], v[230:233], v[50:53]
	v_mfma_f32_16x16x32_bf16 v[42:45], v[190:193], v[230:233], v[42:45]
	v_mfma_f32_16x16x32_bf16 v[42:45], v[186:189], v[226:229], v[42:45]
	v_mfma_f32_16x16x32_bf16 v[26:29], v[186:189], v[234:237], v[26:29]
	v_mfma_f32_16x16x32_bf16 v[26:29], v[190:193], v[238:241], v[26:29]
	v_mfma_f32_16x16x32_bf16 v[34:37], v[182:185], v[238:241], v[34:37]
	v_mfma_f32_16x16x32_bf16 v[34:37], v[178:181], v[234:237], v[34:37]
	v_mfma_f32_16x16x32_bf16 v[46:49], v[166:169], v[234:237], v[46:49]
	v_mfma_f32_16x16x32_bf16 v[46:49], v[174:177], v[238:241], v[46:49]
	v_mfma_f32_16x16x32_bf16 v[54:57], v[162:165], v[238:241], v[54:57]
	v_mfma_f32_16x16x32_bf16 v[54:57], v[158:161], v[234:237], v[54:57]
	v_mfma_f32_16x16x32_bf16 v[38:41], v[158:161], v[242:245], v[38:41]
	v_mfma_f32_16x16x32_bf16 v[38:41], v[162:165], v[246:249], v[38:41]
	v_mfma_f32_16x16x32_bf16 v[30:33], v[174:177], v[246:249], v[30:33]
	v_mfma_f32_16x16x32_bf16 v[30:33], v[166:169], v[242:245], v[30:33]
	v_mfma_f32_16x16x32_bf16 v[18:21], v[178:181], v[242:245], v[18:21]
	v_mfma_f32_16x16x32_bf16 v[18:21], v[182:185], v[246:249], v[18:21]
	v_mfma_f32_16x16x32_bf16 v[10:13], v[190:193], v[246:249], v[10:13]
	v_mfma_f32_16x16x32_bf16 v[10:13], v[186:189], v[242:245], v[10:13]
	v_mfma_f32_16x16x32_bf16 v[2:5], v[186:189], v[250:253], v[2:5]
	v_mfma_f32_16x16x32_bf16 v[2:5], v[190:193], v[142:145], v[2:5]
	v_mfma_f32_16x16x32_bf16 v[6:9], v[182:185], v[142:145], v[6:9]
	v_mfma_f32_16x16x32_bf16 v[6:9], v[178:181], v[250:253], v[6:9]
	v_mfma_f32_16x16x32_bf16 v[14:17], v[166:169], v[250:253], v[14:17]
	v_mfma_f32_16x16x32_bf16 v[14:17], v[174:177], v[142:145], v[14:17]
	v_mfma_f32_16x16x32_bf16 v[22:25], v[162:165], v[142:145], v[22:25]
	v_mfma_f32_16x16x32_bf16 v[22:25], v[158:161], v[250:253], v[22:25]
	s_setprio 0
	s_waitcnt vmcnt(0)
	s_barrier
	s_add_i32 s57, s57, 1
